# SwiGLU epilogue: row scale folded into the exponent and the product (4 fewer packed muls/group), packed +1; on top of opt19/opt18/opt17
# baseline (speedup 1.0000x reference)
.LBB0_479:
	v_lshl_add_u32 v160, s12, 10, v153
	v_lshl_or_b32 v150, s13, 7, v154
	v_lshl_add_u32 v159, s40, 8, v131
	v_ashrrev_i32_e32 v151, 31, v150
	v_mov_b64_e32 v[148:149], s[16:17]
	v_mad_i64_i32 v[164:165], s[12:13], v159, s67, v[148:149]
	v_lshlrev_b64 v[150:151], 1, v[150:151]
	v_lshl_add_u64 v[164:165], v[164:165], 0, v[150:151]
	v_mov_b32_e32 v232, v164
	v_mov_b32_e32 v233, v165
	ds_read_b32 v172, v160
	ds_read_b32 v174, v160 offset:64
	ds_read_b32 v176, v160 offset:128
	ds_read_b32 v178, v160 offset:192
	ds_read_b32 v180, v160 offset:512
	ds_read_b32 v182, v160 offset:576
	ds_read_b32 v184, v160 offset:640
	ds_read_b32 v186, v160 offset:704
	v_mov_b32_e32 v188, 0xbfb8aa3b
	v_mov_b32_e32 v190, 1.0
	v_mov_b32_e32 v191, 1.0
	s_waitcnt lgkmcnt(7)
	v_mul_f32_e32 v234, v188, v172
	v_mul_f32_e32 v236, v172, v172
	v_pk_mul_f32 v[192:193], v[124:125], v[234:235] op_sel_hi:[1,0]
	v_pk_mul_f32 v[194:195], v[126:127], v[234:235] op_sel_hi:[1,0]
	v_pk_mul_f32 v[196:197], v[120:121], v[234:235] op_sel_hi:[1,0]
	v_pk_mul_f32 v[198:199], v[122:123], v[234:235] op_sel_hi:[1,0]
	v_exp_f32_e32 v192, v192
	v_exp_f32_e32 v193, v193
	v_exp_f32_e32 v194, v194
	v_exp_f32_e32 v195, v195
	v_exp_f32_e32 v196, v196
	v_exp_f32_e32 v197, v197
	v_exp_f32_e32 v198, v198
	v_exp_f32_e32 v199, v199
	v_pk_mul_f32 v[124:125], v[124:125], v[116:117]
	v_pk_mul_f32 v[126:127], v[126:127], v[118:119]
	v_pk_mul_f32 v[120:121], v[120:121], v[112:113]
	v_pk_mul_f32 v[122:123], v[122:123], v[114:115]
	v_pk_add_f32 v[192:193], v[192:193], v[190:191]
	v_pk_add_f32 v[194:195], v[194:195], v[190:191]
	v_pk_add_f32 v[196:197], v[196:197], v[190:191]
	v_pk_add_f32 v[198:199], v[198:199], v[190:191]
	v_rcp_f32_e32 v192, v192
	v_rcp_f32_e32 v193, v193
	v_rcp_f32_e32 v194, v194
	v_rcp_f32_e32 v195, v195
	v_rcp_f32_e32 v196, v196
	v_rcp_f32_e32 v197, v197
	v_rcp_f32_e32 v198, v198
	v_rcp_f32_e32 v199, v199
	v_pk_mul_f32 v[124:125], v[124:125], v[236:237] op_sel_hi:[1,0]
	v_pk_mul_f32 v[126:127], v[126:127], v[236:237] op_sel_hi:[1,0]
	v_pk_mul_f32 v[120:121], v[120:121], v[236:237] op_sel_hi:[1,0]
	v_pk_mul_f32 v[122:123], v[122:123], v[236:237] op_sel_hi:[1,0]
	v_pk_mul_f32 v[124:125], v[124:125], v[192:193]
	v_pk_mul_f32 v[126:127], v[126:127], v[194:195]
	v_pk_mul_f32 v[120:121], v[120:121], v[196:197]
	v_pk_mul_f32 v[122:123], v[122:123], v[198:199]
	v_cvt_pk_bf16_f32 v208, v124, v125
	v_cvt_pk_bf16_f32 v209, v126, v127
	v_cvt_pk_bf16_f32 v210, v120, v121
	v_cvt_pk_bf16_f32 v211, v122, v123
	global_store_dwordx4 v[232:233], v[208:211], off
	s_waitcnt lgkmcnt(6)
	v_mul_f32_e32 v234, v188, v174
	v_mul_f32_e32 v236, v174, v174
	v_pk_mul_f32 v[200:201], v[108:109], v[234:235] op_sel_hi:[1,0]
	v_pk_mul_f32 v[202:203], v[110:111], v[234:235] op_sel_hi:[1,0]
	v_pk_mul_f32 v[204:205], v[104:105], v[234:235] op_sel_hi:[1,0]
	v_pk_mul_f32 v[206:207], v[106:107], v[234:235] op_sel_hi:[1,0]
	v_exp_f32_e32 v200, v200
	v_exp_f32_e32 v201, v201
	v_exp_f32_e32 v202, v202
	v_exp_f32_e32 v203, v203
	v_exp_f32_e32 v204, v204
	v_exp_f32_e32 v205, v205
	v_exp_f32_e32 v206, v206
	v_exp_f32_e32 v207, v207
	v_pk_mul_f32 v[108:109], v[108:109], v[100:101]
	v_pk_mul_f32 v[110:111], v[110:111], v[102:103]
	v_pk_mul_f32 v[104:105], v[104:105], v[96:97]
	v_pk_mul_f32 v[106:107], v[106:107], v[98:99]
	v_pk_add_f32 v[200:201], v[200:201], v[190:191]
	v_pk_add_f32 v[202:203], v[202:203], v[190:191]
	v_pk_add_f32 v[204:205], v[204:205], v[190:191]
	v_pk_add_f32 v[206:207], v[206:207], v[190:191]
	v_rcp_f32_e32 v200, v200
	v_rcp_f32_e32 v201, v201
	v_rcp_f32_e32 v202, v202
	v_rcp_f32_e32 v203, v203
	v_rcp_f32_e32 v204, v204
	v_rcp_f32_e32 v205, v205
	v_rcp_f32_e32 v206, v206
	v_rcp_f32_e32 v207, v207
	v_pk_mul_f32 v[108:109], v[108:109], v[236:237] op_sel_hi:[1,0]
	v_pk_mul_f32 v[110:111], v[110:111], v[236:237] op_sel_hi:[1,0]
	v_pk_mul_f32 v[104:105], v[104:105], v[236:237] op_sel_hi:[1,0]
	v_pk_mul_f32 v[106:107], v[106:107], v[236:237] op_sel_hi:[1,0]
	v_pk_mul_f32 v[108:109], v[108:109], v[200:201]
	v_pk_mul_f32 v[110:111], v[110:111], v[202:203]
	v_pk_mul_f32 v[104:105], v[104:105], v[204:205]
	v_pk_mul_f32 v[106:107], v[106:107], v[206:207]
	v_cvt_pk_bf16_f32 v212, v108, v109
	v_cvt_pk_bf16_f32 v213, v110, v111
	v_cvt_pk_bf16_f32 v214, v104, v105
	v_cvt_pk_bf16_f32 v215, v106, v107
	s_mov_b64 s[100:101], 0x16000
	v_lshl_add_u64 v[216:217], v[232:233], 0, s[100:101]
	global_store_dwordx4 v[216:217], v[212:215], off
	s_waitcnt lgkmcnt(5)
	v_mul_f32_e32 v234, v188, v176
	v_mul_f32_e32 v236, v176, v176
	v_pk_mul_f32 v[192:193], v[92:93], v[234:235] op_sel_hi:[1,0]
	v_pk_mul_f32 v[194:195], v[94:95], v[234:235] op_sel_hi:[1,0]
	v_pk_mul_f32 v[196:197], v[88:89], v[234:235] op_sel_hi:[1,0]
	v_pk_mul_f32 v[198:199], v[90:91], v[234:235] op_sel_hi:[1,0]
	v_exp_f32_e32 v192, v192
	v_exp_f32_e32 v193, v193
	v_exp_f32_e32 v194, v194
	v_exp_f32_e32 v195, v195
	v_exp_f32_e32 v196, v196
	v_exp_f32_e32 v197, v197
	v_exp_f32_e32 v198, v198
	v_exp_f32_e32 v199, v199
	v_pk_mul_f32 v[92:93], v[92:93], v[84:85]
	v_pk_mul_f32 v[94:95], v[94:95], v[86:87]
	v_pk_mul_f32 v[88:89], v[88:89], v[80:81]
	v_pk_mul_f32 v[90:91], v[90:91], v[82:83]
	v_pk_add_f32 v[192:193], v[192:193], v[190:191]
	v_pk_add_f32 v[194:195], v[194:195], v[190:191]
	v_pk_add_f32 v[196:197], v[196:197], v[190:191]
	v_pk_add_f32 v[198:199], v[198:199], v[190:191]
	v_rcp_f32_e32 v192, v192
	v_rcp_f32_e32 v193, v193
	v_rcp_f32_e32 v194, v194
	v_rcp_f32_e32 v195, v195
	v_rcp_f32_e32 v196, v196
	v_rcp_f32_e32 v197, v197
	v_rcp_f32_e32 v198, v198
	v_rcp_f32_e32 v199, v199
	v_pk_mul_f32 v[92:93], v[92:93], v[236:237] op_sel_hi:[1,0]
	v_pk_mul_f32 v[94:95], v[94:95], v[236:237] op_sel_hi:[1,0]
	v_pk_mul_f32 v[88:89], v[88:89], v[236:237] op_sel_hi:[1,0]
	v_pk_mul_f32 v[90:91], v[90:91], v[236:237] op_sel_hi:[1,0]
	v_pk_mul_f32 v[92:93], v[92:93], v[192:193]
	v_pk_mul_f32 v[94:95], v[94:95], v[194:195]
	v_pk_mul_f32 v[88:89], v[88:89], v[196:197]
	v_pk_mul_f32 v[90:91], v[90:91], v[198:199]
	v_cvt_pk_bf16_f32 v208, v92, v93
	v_cvt_pk_bf16_f32 v209, v94, v95
	v_cvt_pk_bf16_f32 v210, v88, v89
	v_cvt_pk_bf16_f32 v211, v90, v91
	s_mov_b64 s[100:101], 0x2c000
	v_lshl_add_u64 v[216:217], v[232:233], 0, s[100:101]
	global_store_dwordx4 v[216:217], v[208:211], off
	s_waitcnt lgkmcnt(4)
	v_mul_f32_e32 v234, v188, v178
	v_mul_f32_e32 v236, v178, v178
	v_pk_mul_f32 v[200:201], v[76:77], v[234:235] op_sel_hi:[1,0]
	v_pk_mul_f32 v[202:203], v[78:79], v[234:235] op_sel_hi:[1,0]
	v_pk_mul_f32 v[204:205], v[72:73], v[234:235] op_sel_hi:[1,0]
	v_pk_mul_f32 v[206:207], v[74:75], v[234:235] op_sel_hi:[1,0]
	v_exp_f32_e32 v200, v200
	v_exp_f32_e32 v201, v201
	v_exp_f32_e32 v202, v202
	v_exp_f32_e32 v203, v203
	v_exp_f32_e32 v204, v204
	v_exp_f32_e32 v205, v205
	v_exp_f32_e32 v206, v206
	v_exp_f32_e32 v207, v207
	v_pk_mul_f32 v[76:77], v[76:77], v[68:69]
	v_pk_mul_f32 v[78:79], v[78:79], v[70:71]
	v_pk_mul_f32 v[72:73], v[72:73], v[64:65]
	v_pk_mul_f32 v[74:75], v[74:75], v[66:67]
	v_pk_add_f32 v[200:201], v[200:201], v[190:191]
	v_pk_add_f32 v[202:203], v[202:203], v[190:191]
	v_pk_add_f32 v[204:205], v[204:205], v[190:191]
	v_pk_add_f32 v[206:207], v[206:207], v[190:191]
	v_rcp_f32_e32 v200, v200
	v_rcp_f32_e32 v201, v201
	v_rcp_f32_e32 v202, v202
	v_rcp_f32_e32 v203, v203
	v_rcp_f32_e32 v204, v204
	v_rcp_f32_e32 v205, v205
	v_rcp_f32_e32 v206, v206
	v_rcp_f32_e32 v207, v207
	v_pk_mul_f32 v[76:77], v[76:77], v[236:237] op_sel_hi:[1,0]
	v_pk_mul_f32 v[78:79], v[78:79], v[236:237] op_sel_hi:[1,0]
	v_pk_mul_f32 v[72:73], v[72:73], v[236:237] op_sel_hi:[1,0]
	v_pk_mul_f32 v[74:75], v[74:75], v[236:237] op_sel_hi:[1,0]
	v_pk_mul_f32 v[76:77], v[76:77], v[200:201]
	v_pk_mul_f32 v[78:79], v[78:79], v[202:203]
	v_pk_mul_f32 v[72:73], v[72:73], v[204:205]
	v_pk_mul_f32 v[74:75], v[74:75], v[206:207]
	v_cvt_pk_bf16_f32 v212, v76, v77
	v_cvt_pk_bf16_f32 v213, v78, v79
	v_cvt_pk_bf16_f32 v214, v72, v73
	v_cvt_pk_bf16_f32 v215, v74, v75
	s_mov_b64 s[100:101], 0x42000
	v_lshl_add_u64 v[216:217], v[232:233], 0, s[100:101]
	global_store_dwordx4 v[216:217], v[212:215], off
	s_waitcnt lgkmcnt(3)
	v_mul_f32_e32 v234, v188, v180
	v_mul_f32_e32 v236, v180, v180
	v_pk_mul_f32 v[192:193], v[60:61], v[234:235] op_sel_hi:[1,0]
	v_pk_mul_f32 v[194:195], v[62:63], v[234:235] op_sel_hi:[1,0]
	v_pk_mul_f32 v[196:197], v[56:57], v[234:235] op_sel_hi:[1,0]
	v_pk_mul_f32 v[198:199], v[58:59], v[234:235] op_sel_hi:[1,0]
	v_exp_f32_e32 v192, v192
	v_exp_f32_e32 v193, v193
	v_exp_f32_e32 v194, v194
	v_exp_f32_e32 v195, v195
	v_exp_f32_e32 v196, v196
	v_exp_f32_e32 v197, v197
	v_exp_f32_e32 v198, v198
	v_exp_f32_e32 v199, v199
	v_pk_mul_f32 v[60:61], v[60:61], v[52:53]
	v_pk_mul_f32 v[62:63], v[62:63], v[54:55]
	v_pk_mul_f32 v[56:57], v[56:57], v[48:49]
	v_pk_mul_f32 v[58:59], v[58:59], v[50:51]
	v_pk_add_f32 v[192:193], v[192:193], v[190:191]
	v_pk_add_f32 v[194:195], v[194:195], v[190:191]
	v_pk_add_f32 v[196:197], v[196:197], v[190:191]
	v_pk_add_f32 v[198:199], v[198:199], v[190:191]
	v_rcp_f32_e32 v192, v192
	v_rcp_f32_e32 v193, v193
	v_rcp_f32_e32 v194, v194
	v_rcp_f32_e32 v195, v195
	v_rcp_f32_e32 v196, v196
	v_rcp_f32_e32 v197, v197
	v_rcp_f32_e32 v198, v198
	v_rcp_f32_e32 v199, v199
	v_pk_mul_f32 v[60:61], v[60:61], v[236:237] op_sel_hi:[1,0]
	v_pk_mul_f32 v[62:63], v[62:63], v[236:237] op_sel_hi:[1,0]
	v_pk_mul_f32 v[56:57], v[56:57], v[236:237] op_sel_hi:[1,0]
	v_pk_mul_f32 v[58:59], v[58:59], v[236:237] op_sel_hi:[1,0]
	v_pk_mul_f32 v[60:61], v[60:61], v[192:193]
	v_pk_mul_f32 v[62:63], v[62:63], v[194:195]
	v_pk_mul_f32 v[56:57], v[56:57], v[196:197]
	v_pk_mul_f32 v[58:59], v[58:59], v[198:199]
	v_cvt_pk_bf16_f32 v208, v60, v61
	v_cvt_pk_bf16_f32 v209, v62, v63
	v_cvt_pk_bf16_f32 v210, v56, v57
	v_cvt_pk_bf16_f32 v211, v58, v59
	s_mov_b64 s[100:101], 0xb0000
	v_lshl_add_u64 v[216:217], v[232:233], 0, s[100:101]
	global_store_dwordx4 v[216:217], v[208:211], off
	s_waitcnt lgkmcnt(2)
	v_mul_f32_e32 v234, v188, v182
	v_mul_f32_e32 v236, v182, v182
	v_pk_mul_f32 v[200:201], v[44:45], v[234:235] op_sel_hi:[1,0]
	v_pk_mul_f32 v[202:203], v[46:47], v[234:235] op_sel_hi:[1,0]
	v_pk_mul_f32 v[204:205], v[40:41], v[234:235] op_sel_hi:[1,0]
	v_pk_mul_f32 v[206:207], v[42:43], v[234:235] op_sel_hi:[1,0]
	v_exp_f32_e32 v200, v200
	v_exp_f32_e32 v201, v201
	v_exp_f32_e32 v202, v202
	v_exp_f32_e32 v203, v203
	v_exp_f32_e32 v204, v204
	v_exp_f32_e32 v205, v205
	v_exp_f32_e32 v206, v206
	v_exp_f32_e32 v207, v207
	v_pk_mul_f32 v[44:45], v[44:45], v[36:37]
	v_pk_mul_f32 v[46:47], v[46:47], v[38:39]
	v_pk_mul_f32 v[40:41], v[40:41], v[32:33]
	v_pk_mul_f32 v[42:43], v[42:43], v[34:35]
	v_pk_add_f32 v[200:201], v[200:201], v[190:191]
	v_pk_add_f32 v[202:203], v[202:203], v[190:191]
	v_pk_add_f32 v[204:205], v[204:205], v[190:191]
	v_pk_add_f32 v[206:207], v[206:207], v[190:191]
	v_rcp_f32_e32 v200, v200
	v_rcp_f32_e32 v201, v201
	v_rcp_f32_e32 v202, v202
	v_rcp_f32_e32 v203, v203
	v_rcp_f32_e32 v204, v204
	v_rcp_f32_e32 v205, v205
	v_rcp_f32_e32 v206, v206
	v_rcp_f32_e32 v207, v207
	v_pk_mul_f32 v[44:45], v[44:45], v[236:237] op_sel_hi:[1,0]
	v_pk_mul_f32 v[46:47], v[46:47], v[236:237] op_sel_hi:[1,0]
	v_pk_mul_f32 v[40:41], v[40:41], v[236:237] op_sel_hi:[1,0]
	v_pk_mul_f32 v[42:43], v[42:43], v[236:237] op_sel_hi:[1,0]
	v_pk_mul_f32 v[44:45], v[44:45], v[200:201]
	v_pk_mul_f32 v[46:47], v[46:47], v[202:203]
	v_pk_mul_f32 v[40:41], v[40:41], v[204:205]
	v_pk_mul_f32 v[42:43], v[42:43], v[206:207]
	v_cvt_pk_bf16_f32 v212, v44, v45
	v_cvt_pk_bf16_f32 v213, v46, v47
	v_cvt_pk_bf16_f32 v214, v40, v41
	v_cvt_pk_bf16_f32 v215, v42, v43
	s_mov_b64 s[100:101], 0xc6000
	v_lshl_add_u64 v[216:217], v[232:233], 0, s[100:101]
	global_store_dwordx4 v[216:217], v[212:215], off
	s_waitcnt lgkmcnt(1)
	v_mul_f32_e32 v234, v188, v184
	v_mul_f32_e32 v236, v184, v184
	v_pk_mul_f32 v[192:193], v[28:29], v[234:235] op_sel_hi:[1,0]
	v_pk_mul_f32 v[194:195], v[30:31], v[234:235] op_sel_hi:[1,0]
	v_pk_mul_f32 v[196:197], v[24:25], v[234:235] op_sel_hi:[1,0]
	v_pk_mul_f32 v[198:199], v[26:27], v[234:235] op_sel_hi:[1,0]
	v_exp_f32_e32 v192, v192
	v_exp_f32_e32 v193, v193
	v_exp_f32_e32 v194, v194
	v_exp_f32_e32 v195, v195
	v_exp_f32_e32 v196, v196
	v_exp_f32_e32 v197, v197
	v_exp_f32_e32 v198, v198
	v_exp_f32_e32 v199, v199
	v_pk_mul_f32 v[28:29], v[28:29], v[20:21]
	v_pk_mul_f32 v[30:31], v[30:31], v[22:23]
	v_pk_mul_f32 v[24:25], v[24:25], v[16:17]
	v_pk_mul_f32 v[26:27], v[26:27], v[18:19]
	v_pk_add_f32 v[192:193], v[192:193], v[190:191]
	v_pk_add_f32 v[194:195], v[194:195], v[190:191]
	v_pk_add_f32 v[196:197], v[196:197], v[190:191]
	v_pk_add_f32 v[198:199], v[198:199], v[190:191]
	v_rcp_f32_e32 v192, v192
	v_rcp_f32_e32 v193, v193
	v_rcp_f32_e32 v194, v194
	v_rcp_f32_e32 v195, v195
	v_rcp_f32_e32 v196, v196
	v_rcp_f32_e32 v197, v197
	v_rcp_f32_e32 v198, v198
	v_rcp_f32_e32 v199, v199
	v_pk_mul_f32 v[28:29], v[28:29], v[236:237] op_sel_hi:[1,0]
	v_pk_mul_f32 v[30:31], v[30:31], v[236:237] op_sel_hi:[1,0]
	v_pk_mul_f32 v[24:25], v[24:25], v[236:237] op_sel_hi:[1,0]
	v_pk_mul_f32 v[26:27], v[26:27], v[236:237] op_sel_hi:[1,0]
	v_pk_mul_f32 v[28:29], v[28:29], v[192:193]
	v_pk_mul_f32 v[30:31], v[30:31], v[194:195]
	v_pk_mul_f32 v[24:25], v[24:25], v[196:197]
	v_pk_mul_f32 v[26:27], v[26:27], v[198:199]
	v_cvt_pk_bf16_f32 v208, v28, v29
	v_cvt_pk_bf16_f32 v209, v30, v31
	v_cvt_pk_bf16_f32 v210, v24, v25
	v_cvt_pk_bf16_f32 v211, v26, v27
	s_mov_b64 s[100:101], 0xdc000
	v_lshl_add_u64 v[216:217], v[232:233], 0, s[100:101]
	global_store_dwordx4 v[216:217], v[208:211], off
	s_waitcnt lgkmcnt(0)
	v_mul_f32_e32 v234, v188, v186
	v_mul_f32_e32 v236, v186, v186
	v_pk_mul_f32 v[200:201], v[12:13], v[234:235] op_sel_hi:[1,0]
	v_pk_mul_f32 v[202:203], v[14:15], v[234:235] op_sel_hi:[1,0]
	v_pk_mul_f32 v[204:205], v[8:9], v[234:235] op_sel_hi:[1,0]
	v_pk_mul_f32 v[206:207], v[10:11], v[234:235] op_sel_hi:[1,0]
	v_exp_f32_e32 v200, v200
	v_exp_f32_e32 v201, v201
	v_exp_f32_e32 v202, v202
	v_exp_f32_e32 v203, v203
	v_exp_f32_e32 v204, v204
	v_exp_f32_e32 v205, v205
	v_exp_f32_e32 v206, v206
	v_exp_f32_e32 v207, v207
	v_pk_mul_f32 v[12:13], v[12:13], v[4:5]
	v_pk_mul_f32 v[14:15], v[14:15], v[6:7]
	v_pk_mul_f32 v[8:9], v[8:9], v[0:1]
	v_pk_mul_f32 v[10:11], v[10:11], v[2:3]
	v_pk_add_f32 v[200:201], v[200:201], v[190:191]
	v_pk_add_f32 v[202:203], v[202:203], v[190:191]
	v_pk_add_f32 v[204:205], v[204:205], v[190:191]
	v_pk_add_f32 v[206:207], v[206:207], v[190:191]
	v_rcp_f32_e32 v200, v200
	v_rcp_f32_e32 v201, v201
	v_rcp_f32_e32 v202, v202
	v_rcp_f32_e32 v203, v203
	v_rcp_f32_e32 v204, v204
	v_rcp_f32_e32 v205, v205
	v_rcp_f32_e32 v206, v206
	v_rcp_f32_e32 v207, v207
	v_pk_mul_f32 v[12:13], v[12:13], v[236:237] op_sel_hi:[1,0]
	v_pk_mul_f32 v[14:15], v[14:15], v[236:237] op_sel_hi:[1,0]
	v_pk_mul_f32 v[8:9], v[8:9], v[236:237] op_sel_hi:[1,0]
	v_pk_mul_f32 v[10:11], v[10:11], v[236:237] op_sel_hi:[1,0]
	v_pk_mul_f32 v[12:13], v[12:13], v[200:201]
	v_pk_mul_f32 v[14:15], v[14:15], v[202:203]
	v_pk_mul_f32 v[8:9], v[8:9], v[204:205]
	v_pk_mul_f32 v[10:11], v[10:11], v[206:207]
	v_cvt_pk_bf16_f32 v212, v12, v13
	v_cvt_pk_bf16_f32 v213, v14, v15
	v_cvt_pk_bf16_f32 v214, v8, v9
	v_cvt_pk_bf16_f32 v215, v10, v11
	s_mov_b64 s[100:101], 0xf2000
	v_lshl_add_u64 v[216:217], v[232:233], 0, s[100:101]
	global_store_dwordx4 v[216:217], v[212:215], off
	s_andn2_b64 vcc, exec, s[4:5]
	s_mov_b64 s[4:5], -1
	s_cbranch_vccnz .LBB0_472
	s_andn2_b64 vcc, exec, s[0:1]
	s_cbranch_vccnz .LBB0_471
	s_nop 0
	s_branch .LBB0_471

.LBB0_1062:
	v_lshl_add_u32 v160, s12, 10, v153
	v_lshl_or_b32 v150, s13, 7, v154
	v_lshl_add_u32 v159, s30, 8, v131
	v_ashrrev_i32_e32 v151, 31, v150
	v_mov_b64_e32 v[148:149], s[16:17]
	v_mad_i64_i32 v[164:165], s[12:13], v159, s59, v[148:149]
	v_lshlrev_b64 v[150:151], 1, v[150:151]
	v_lshl_add_u64 v[164:165], v[164:165], 0, v[150:151]
	v_mov_b32_e32 v232, v164
	v_mov_b32_e32 v233, v165
	ds_read_b32 v172, v160
	ds_read_b32 v174, v160 offset:64
	ds_read_b32 v176, v160 offset:128
	ds_read_b32 v178, v160 offset:192
	ds_read_b32 v180, v160 offset:512
	ds_read_b32 v182, v160 offset:576
	ds_read_b32 v184, v160 offset:640
	ds_read_b32 v186, v160 offset:704
	v_mov_b32_e32 v188, 0xbfb8aa3b
	v_mov_b32_e32 v190, 1.0
	v_mov_b32_e32 v191, 1.0
	s_waitcnt lgkmcnt(7)
	v_mul_f32_e32 v234, v188, v172
	v_mul_f32_e32 v236, v172, v172
	v_pk_mul_f32 v[192:193], v[124:125], v[234:235] op_sel_hi:[1,0]
	v_pk_mul_f32 v[194:195], v[126:127], v[234:235] op_sel_hi:[1,0]
	v_pk_mul_f32 v[196:197], v[120:121], v[234:235] op_sel_hi:[1,0]
	v_pk_mul_f32 v[198:199], v[122:123], v[234:235] op_sel_hi:[1,0]
	v_exp_f32_e32 v192, v192
	v_exp_f32_e32 v193, v193
	v_exp_f32_e32 v194, v194
	v_exp_f32_e32 v195, v195
	v_exp_f32_e32 v196, v196
	v_exp_f32_e32 v197, v197
	v_exp_f32_e32 v198, v198
	v_exp_f32_e32 v199, v199
	v_pk_mul_f32 v[124:125], v[124:125], v[116:117]
	v_pk_mul_f32 v[126:127], v[126:127], v[118:119]
	v_pk_mul_f32 v[120:121], v[120:121], v[112:113]
	v_pk_mul_f32 v[122:123], v[122:123], v[114:115]
	v_pk_add_f32 v[192:193], v[192:193], v[190:191]
	v_pk_add_f32 v[194:195], v[194:195], v[190:191]
	v_pk_add_f32 v[196:197], v[196:197], v[190:191]
	v_pk_add_f32 v[198:199], v[198:199], v[190:191]
	v_rcp_f32_e32 v192, v192
	v_rcp_f32_e32 v193, v193
	v_rcp_f32_e32 v194, v194
	v_rcp_f32_e32 v195, v195
	v_rcp_f32_e32 v196, v196
	v_rcp_f32_e32 v197, v197
	v_rcp_f32_e32 v198, v198
	v_rcp_f32_e32 v199, v199
	v_pk_mul_f32 v[124:125], v[124:125], v[236:237] op_sel_hi:[1,0]
	v_pk_mul_f32 v[126:127], v[126:127], v[236:237] op_sel_hi:[1,0]
	v_pk_mul_f32 v[120:121], v[120:121], v[236:237] op_sel_hi:[1,0]
	v_pk_mul_f32 v[122:123], v[122:123], v[236:237] op_sel_hi:[1,0]
	v_pk_mul_f32 v[124:125], v[124:125], v[192:193]
	v_pk_mul_f32 v[126:127], v[126:127], v[194:195]
	v_pk_mul_f32 v[120:121], v[120:121], v[196:197]
	v_pk_mul_f32 v[122:123], v[122:123], v[198:199]
	v_cvt_pk_bf16_f32 v208, v124, v125
	v_cvt_pk_bf16_f32 v209, v126, v127
	v_cvt_pk_bf16_f32 v210, v120, v121
	v_cvt_pk_bf16_f32 v211, v122, v123
	global_store_dwordx4 v[232:233], v[208:211], off
	s_waitcnt lgkmcnt(6)
	v_mul_f32_e32 v234, v188, v174
	v_mul_f32_e32 v236, v174, v174
	v_pk_mul_f32 v[200:201], v[108:109], v[234:235] op_sel_hi:[1,0]
	v_pk_mul_f32 v[202:203], v[110:111], v[234:235] op_sel_hi:[1,0]
	v_pk_mul_f32 v[204:205], v[104:105], v[234:235] op_sel_hi:[1,0]
	v_pk_mul_f32 v[206:207], v[106:107], v[234:235] op_sel_hi:[1,0]
	v_exp_f32_e32 v200, v200
	v_exp_f32_e32 v201, v201
	v_exp_f32_e32 v202, v202
	v_exp_f32_e32 v203, v203
	v_exp_f32_e32 v204, v204
	v_exp_f32_e32 v205, v205
	v_exp_f32_e32 v206, v206
	v_exp_f32_e32 v207, v207
	v_pk_mul_f32 v[108:109], v[108:109], v[100:101]
	v_pk_mul_f32 v[110:111], v[110:111], v[102:103]
	v_pk_mul_f32 v[104:105], v[104:105], v[96:97]
	v_pk_mul_f32 v[106:107], v[106:107], v[98:99]
	v_pk_add_f32 v[200:201], v[200:201], v[190:191]
	v_pk_add_f32 v[202:203], v[202:203], v[190:191]
	v_pk_add_f32 v[204:205], v[204:205], v[190:191]
	v_pk_add_f32 v[206:207], v[206:207], v[190:191]
	v_rcp_f32_e32 v200, v200
	v_rcp_f32_e32 v201, v201
	v_rcp_f32_e32 v202, v202
	v_rcp_f32_e32 v203, v203
	v_rcp_f32_e32 v204, v204
	v_rcp_f32_e32 v205, v205
	v_rcp_f32_e32 v206, v206
	v_rcp_f32_e32 v207, v207
	v_pk_mul_f32 v[108:109], v[108:109], v[236:237] op_sel_hi:[1,0]
	v_pk_mul_f32 v[110:111], v[110:111], v[236:237] op_sel_hi:[1,0]
	v_pk_mul_f32 v[104:105], v[104:105], v[236:237] op_sel_hi:[1,0]
	v_pk_mul_f32 v[106:107], v[106:107], v[236:237] op_sel_hi:[1,0]
	v_pk_mul_f32 v[108:109], v[108:109], v[200:201]
	v_pk_mul_f32 v[110:111], v[110:111], v[202:203]
	v_pk_mul_f32 v[104:105], v[104:105], v[204:205]
	v_pk_mul_f32 v[106:107], v[106:107], v[206:207]
	v_cvt_pk_bf16_f32 v212, v108, v109
	v_cvt_pk_bf16_f32 v213, v110, v111
	v_cvt_pk_bf16_f32 v214, v104, v105
	v_cvt_pk_bf16_f32 v215, v106, v107
	s_mov_b64 s[100:101], 0x16000
	v_lshl_add_u64 v[216:217], v[232:233], 0, s[100:101]
	global_store_dwordx4 v[216:217], v[212:215], off
	s_waitcnt lgkmcnt(5)
	v_mul_f32_e32 v234, v188, v176
	v_mul_f32_e32 v236, v176, v176
	v_pk_mul_f32 v[192:193], v[92:93], v[234:235] op_sel_hi:[1,0]
	v_pk_mul_f32 v[194:195], v[94:95], v[234:235] op_sel_hi:[1,0]
	v_pk_mul_f32 v[196:197], v[88:89], v[234:235] op_sel_hi:[1,0]
	v_pk_mul_f32 v[198:199], v[90:91], v[234:235] op_sel_hi:[1,0]
	v_exp_f32_e32 v192, v192
	v_exp_f32_e32 v193, v193
	v_exp_f32_e32 v194, v194
	v_exp_f32_e32 v195, v195
	v_exp_f32_e32 v196, v196
	v_exp_f32_e32 v197, v197
	v_exp_f32_e32 v198, v198
	v_exp_f32_e32 v199, v199
	v_pk_mul_f32 v[92:93], v[92:93], v[84:85]
	v_pk_mul_f32 v[94:95], v[94:95], v[86:87]
	v_pk_mul_f32 v[88:89], v[88:89], v[80:81]
	v_pk_mul_f32 v[90:91], v[90:91], v[82:83]
	v_pk_add_f32 v[192:193], v[192:193], v[190:191]
	v_pk_add_f32 v[194:195], v[194:195], v[190:191]
	v_pk_add_f32 v[196:197], v[196:197], v[190:191]
	v_pk_add_f32 v[198:199], v[198:199], v[190:191]
	v_rcp_f32_e32 v192, v192
	v_rcp_f32_e32 v193, v193
	v_rcp_f32_e32 v194, v194
	v_rcp_f32_e32 v195, v195
	v_rcp_f32_e32 v196, v196
	v_rcp_f32_e32 v197, v197
	v_rcp_f32_e32 v198, v198
	v_rcp_f32_e32 v199, v199
	v_pk_mul_f32 v[92:93], v[92:93], v[236:237] op_sel_hi:[1,0]
	v_pk_mul_f32 v[94:95], v[94:95], v[236:237] op_sel_hi:[1,0]
	v_pk_mul_f32 v[88:89], v[88:89], v[236:237] op_sel_hi:[1,0]
	v_pk_mul_f32 v[90:91], v[90:91], v[236:237] op_sel_hi:[1,0]
	v_pk_mul_f32 v[92:93], v[92:93], v[192:193]
	v_pk_mul_f32 v[94:95], v[94:95], v[194:195]
	v_pk_mul_f32 v[88:89], v[88:89], v[196:197]
	v_pk_mul_f32 v[90:91], v[90:91], v[198:199]
	v_cvt_pk_bf16_f32 v208, v92, v93
	v_cvt_pk_bf16_f32 v209, v94, v95
	v_cvt_pk_bf16_f32 v210, v88, v89
	v_cvt_pk_bf16_f32 v211, v90, v91
	s_mov_b64 s[100:101], 0x2c000
	v_lshl_add_u64 v[216:217], v[232:233], 0, s[100:101]
	global_store_dwordx4 v[216:217], v[208:211], off
	s_waitcnt lgkmcnt(4)
	v_mul_f32_e32 v234, v188, v178
	v_mul_f32_e32 v236, v178, v178
	v_pk_mul_f32 v[200:201], v[76:77], v[234:235] op_sel_hi:[1,0]
	v_pk_mul_f32 v[202:203], v[78:79], v[234:235] op_sel_hi:[1,0]
	v_pk_mul_f32 v[204:205], v[72:73], v[234:235] op_sel_hi:[1,0]
	v_pk_mul_f32 v[206:207], v[74:75], v[234:235] op_sel_hi:[1,0]
	v_exp_f32_e32 v200, v200
	v_exp_f32_e32 v201, v201
	v_exp_f32_e32 v202, v202
	v_exp_f32_e32 v203, v203
	v_exp_f32_e32 v204, v204
	v_exp_f32_e32 v205, v205
	v_exp_f32_e32 v206, v206
	v_exp_f32_e32 v207, v207
	v_pk_mul_f32 v[76:77], v[76:77], v[68:69]
	v_pk_mul_f32 v[78:79], v[78:79], v[70:71]
	v_pk_mul_f32 v[72:73], v[72:73], v[64:65]
	v_pk_mul_f32 v[74:75], v[74:75], v[66:67]
	v_pk_add_f32 v[200:201], v[200:201], v[190:191]
	v_pk_add_f32 v[202:203], v[202:203], v[190:191]
	v_pk_add_f32 v[204:205], v[204:205], v[190:191]
	v_pk_add_f32 v[206:207], v[206:207], v[190:191]
	v_rcp_f32_e32 v200, v200
	v_rcp_f32_e32 v201, v201
	v_rcp_f32_e32 v202, v202
	v_rcp_f32_e32 v203, v203
	v_rcp_f32_e32 v204, v204
	v_rcp_f32_e32 v205, v205
	v_rcp_f32_e32 v206, v206
	v_rcp_f32_e32 v207, v207
	v_pk_mul_f32 v[76:77], v[76:77], v[236:237] op_sel_hi:[1,0]
	v_pk_mul_f32 v[78:79], v[78:79], v[236:237] op_sel_hi:[1,0]
	v_pk_mul_f32 v[72:73], v[72:73], v[236:237] op_sel_hi:[1,0]
	v_pk_mul_f32 v[74:75], v[74:75], v[236:237] op_sel_hi:[1,0]
	v_pk_mul_f32 v[76:77], v[76:77], v[200:201]
	v_pk_mul_f32 v[78:79], v[78:79], v[202:203]
	v_pk_mul_f32 v[72:73], v[72:73], v[204:205]
	v_pk_mul_f32 v[74:75], v[74:75], v[206:207]
	v_cvt_pk_bf16_f32 v212, v76, v77
	v_cvt_pk_bf16_f32 v213, v78, v79
	v_cvt_pk_bf16_f32 v214, v72, v73
	v_cvt_pk_bf16_f32 v215, v74, v75
	s_mov_b64 s[100:101], 0x42000
	v_lshl_add_u64 v[216:217], v[232:233], 0, s[100:101]
	global_store_dwordx4 v[216:217], v[212:215], off
	s_waitcnt lgkmcnt(3)
	v_mul_f32_e32 v234, v188, v180
	v_mul_f32_e32 v236, v180, v180
	v_pk_mul_f32 v[192:193], v[60:61], v[234:235] op_sel_hi:[1,0]
	v_pk_mul_f32 v[194:195], v[62:63], v[234:235] op_sel_hi:[1,0]
	v_pk_mul_f32 v[196:197], v[56:57], v[234:235] op_sel_hi:[1,0]
	v_pk_mul_f32 v[198:199], v[58:59], v[234:235] op_sel_hi:[1,0]
	v_exp_f32_e32 v192, v192
	v_exp_f32_e32 v193, v193
	v_exp_f32_e32 v194, v194
	v_exp_f32_e32 v195, v195
	v_exp_f32_e32 v196, v196
	v_exp_f32_e32 v197, v197
	v_exp_f32_e32 v198, v198
	v_exp_f32_e32 v199, v199
	v_pk_mul_f32 v[60:61], v[60:61], v[52:53]
	v_pk_mul_f32 v[62:63], v[62:63], v[54:55]
	v_pk_mul_f32 v[56:57], v[56:57], v[48:49]
	v_pk_mul_f32 v[58:59], v[58:59], v[50:51]
	v_pk_add_f32 v[192:193], v[192:193], v[190:191]
	v_pk_add_f32 v[194:195], v[194:195], v[190:191]
	v_pk_add_f32 v[196:197], v[196:197], v[190:191]
	v_pk_add_f32 v[198:199], v[198:199], v[190:191]
	v_rcp_f32_e32 v192, v192
	v_rcp_f32_e32 v193, v193
	v_rcp_f32_e32 v194, v194
	v_rcp_f32_e32 v195, v195
	v_rcp_f32_e32 v196, v196
	v_rcp_f32_e32 v197, v197
	v_rcp_f32_e32 v198, v198
	v_rcp_f32_e32 v199, v199
	v_pk_mul_f32 v[60:61], v[60:61], v[236:237] op_sel_hi:[1,0]
	v_pk_mul_f32 v[62:63], v[62:63], v[236:237] op_sel_hi:[1,0]
	v_pk_mul_f32 v[56:57], v[56:57], v[236:237] op_sel_hi:[1,0]
	v_pk_mul_f32 v[58:59], v[58:59], v[236:237] op_sel_hi:[1,0]
	v_pk_mul_f32 v[60:61], v[60:61], v[192:193]
	v_pk_mul_f32 v[62:63], v[62:63], v[194:195]
	v_pk_mul_f32 v[56:57], v[56:57], v[196:197]
	v_pk_mul_f32 v[58:59], v[58:59], v[198:199]
	v_cvt_pk_bf16_f32 v208, v60, v61
	v_cvt_pk_bf16_f32 v209, v62, v63
	v_cvt_pk_bf16_f32 v210, v56, v57
	v_cvt_pk_bf16_f32 v211, v58, v59
	s_mov_b64 s[100:101], 0xb0000
	v_lshl_add_u64 v[216:217], v[232:233], 0, s[100:101]
	global_store_dwordx4 v[216:217], v[208:211], off
	s_waitcnt lgkmcnt(2)
	v_mul_f32_e32 v234, v188, v182
	v_mul_f32_e32 v236, v182, v182
	v_pk_mul_f32 v[200:201], v[44:45], v[234:235] op_sel_hi:[1,0]
	v_pk_mul_f32 v[202:203], v[46:47], v[234:235] op_sel_hi:[1,0]
	v_pk_mul_f32 v[204:205], v[40:41], v[234:235] op_sel_hi:[1,0]
	v_pk_mul_f32 v[206:207], v[42:43], v[234:235] op_sel_hi:[1,0]
	v_exp_f32_e32 v200, v200
	v_exp_f32_e32 v201, v201
	v_exp_f32_e32 v202, v202
	v_exp_f32_e32 v203, v203
	v_exp_f32_e32 v204, v204
	v_exp_f32_e32 v205, v205
	v_exp_f32_e32 v206, v206
	v_exp_f32_e32 v207, v207
	v_pk_mul_f32 v[44:45], v[44:45], v[36:37]
	v_pk_mul_f32 v[46:47], v[46:47], v[38:39]
	v_pk_mul_f32 v[40:41], v[40:41], v[32:33]
	v_pk_mul_f32 v[42:43], v[42:43], v[34:35]
	v_pk_add_f32 v[200:201], v[200:201], v[190:191]
	v_pk_add_f32 v[202:203], v[202:203], v[190:191]
	v_pk_add_f32 v[204:205], v[204:205], v[190:191]
	v_pk_add_f32 v[206:207], v[206:207], v[190:191]
	v_rcp_f32_e32 v200, v200
	v_rcp_f32_e32 v201, v201
	v_rcp_f32_e32 v202, v202
	v_rcp_f32_e32 v203, v203
	v_rcp_f32_e32 v204, v204
	v_rcp_f32_e32 v205, v205
	v_rcp_f32_e32 v206, v206
	v_rcp_f32_e32 v207, v207
	v_pk_mul_f32 v[44:45], v[44:45], v[236:237] op_sel_hi:[1,0]
	v_pk_mul_f32 v[46:47], v[46:47], v[236:237] op_sel_hi:[1,0]
	v_pk_mul_f32 v[40:41], v[40:41], v[236:237] op_sel_hi:[1,0]
	v_pk_mul_f32 v[42:43], v[42:43], v[236:237] op_sel_hi:[1,0]
	v_pk_mul_f32 v[44:45], v[44:45], v[200:201]
	v_pk_mul_f32 v[46:47], v[46:47], v[202:203]
	v_pk_mul_f32 v[40:41], v[40:41], v[204:205]
	v_pk_mul_f32 v[42:43], v[42:43], v[206:207]
	v_cvt_pk_bf16_f32 v212, v44, v45
	v_cvt_pk_bf16_f32 v213, v46, v47
	v_cvt_pk_bf16_f32 v214, v40, v41
	v_cvt_pk_bf16_f32 v215, v42, v43
	s_mov_b64 s[100:101], 0xc6000
	v_lshl_add_u64 v[216:217], v[232:233], 0, s[100:101]
	global_store_dwordx4 v[216:217], v[212:215], off
	s_waitcnt lgkmcnt(1)
	v_mul_f32_e32 v234, v188, v184
	v_mul_f32_e32 v236, v184, v184
	v_pk_mul_f32 v[192:193], v[28:29], v[234:235] op_sel_hi:[1,0]
	v_pk_mul_f32 v[194:195], v[30:31], v[234:235] op_sel_hi:[1,0]
	v_pk_mul_f32 v[196:197], v[24:25], v[234:235] op_sel_hi:[1,0]
	v_pk_mul_f32 v[198:199], v[26:27], v[234:235] op_sel_hi:[1,0]
	v_exp_f32_e32 v192, v192
	v_exp_f32_e32 v193, v193
	v_exp_f32_e32 v194, v194
	v_exp_f32_e32 v195, v195
	v_exp_f32_e32 v196, v196
	v_exp_f32_e32 v197, v197
	v_exp_f32_e32 v198, v198
	v_exp_f32_e32 v199, v199
	v_pk_mul_f32 v[28:29], v[28:29], v[20:21]
	v_pk_mul_f32 v[30:31], v[30:31], v[22:23]
	v_pk_mul_f32 v[24:25], v[24:25], v[16:17]
	v_pk_mul_f32 v[26:27], v[26:27], v[18:19]
	v_pk_add_f32 v[192:193], v[192:193], v[190:191]
	v_pk_add_f32 v[194:195], v[194:195], v[190:191]
	v_pk_add_f32 v[196:197], v[196:197], v[190:191]
	v_pk_add_f32 v[198:199], v[198:199], v[190:191]
	v_rcp_f32_e32 v192, v192
	v_rcp_f32_e32 v193, v193
	v_rcp_f32_e32 v194, v194
	v_rcp_f32_e32 v195, v195
	v_rcp_f32_e32 v196, v196
	v_rcp_f32_e32 v197, v197
	v_rcp_f32_e32 v198, v198
	v_rcp_f32_e32 v199, v199
	v_pk_mul_f32 v[28:29], v[28:29], v[236:237] op_sel_hi:[1,0]
	v_pk_mul_f32 v[30:31], v[30:31], v[236:237] op_sel_hi:[1,0]
	v_pk_mul_f32 v[24:25], v[24:25], v[236:237] op_sel_hi:[1,0]
	v_pk_mul_f32 v[26:27], v[26:27], v[236:237] op_sel_hi:[1,0]
	v_pk_mul_f32 v[28:29], v[28:29], v[192:193]
	v_pk_mul_f32 v[30:31], v[30:31], v[194:195]
	v_pk_mul_f32 v[24:25], v[24:25], v[196:197]
	v_pk_mul_f32 v[26:27], v[26:27], v[198:199]
	v_cvt_pk_bf16_f32 v208, v28, v29
	v_cvt_pk_bf16_f32 v209, v30, v31
	v_cvt_pk_bf16_f32 v210, v24, v25
	v_cvt_pk_bf16_f32 v211, v26, v27
	s_mov_b64 s[100:101], 0xdc000
	v_lshl_add_u64 v[216:217], v[232:233], 0, s[100:101]
	global_store_dwordx4 v[216:217], v[208:211], off
	s_waitcnt lgkmcnt(0)
	v_mul_f32_e32 v234, v188, v186
	v_mul_f32_e32 v236, v186, v186
	v_pk_mul_f32 v[200:201], v[12:13], v[234:235] op_sel_hi:[1,0]
	v_pk_mul_f32 v[202:203], v[14:15], v[234:235] op_sel_hi:[1,0]
	v_pk_mul_f32 v[204:205], v[8:9], v[234:235] op_sel_hi:[1,0]
	v_pk_mul_f32 v[206:207], v[10:11], v[234:235] op_sel_hi:[1,0]
	v_exp_f32_e32 v200, v200
	v_exp_f32_e32 v201, v201
	v_exp_f32_e32 v202, v202
	v_exp_f32_e32 v203, v203
	v_exp_f32_e32 v204, v204
	v_exp_f32_e32 v205, v205
	v_exp_f32_e32 v206, v206
	v_exp_f32_e32 v207, v207
	v_pk_mul_f32 v[12:13], v[12:13], v[4:5]
	v_pk_mul_f32 v[14:15], v[14:15], v[6:7]
	v_pk_mul_f32 v[8:9], v[8:9], v[0:1]
	v_pk_mul_f32 v[10:11], v[10:11], v[2:3]
	v_pk_add_f32 v[200:201], v[200:201], v[190:191]
	v_pk_add_f32 v[202:203], v[202:203], v[190:191]
	v_pk_add_f32 v[204:205], v[204:205], v[190:191]
	v_pk_add_f32 v[206:207], v[206:207], v[190:191]
	v_rcp_f32_e32 v200, v200
	v_rcp_f32_e32 v201, v201
	v_rcp_f32_e32 v202, v202
	v_rcp_f32_e32 v203, v203
	v_rcp_f32_e32 v204, v204
	v_rcp_f32_e32 v205, v205
	v_rcp_f32_e32 v206, v206
	v_rcp_f32_e32 v207, v207
	v_pk_mul_f32 v[12:13], v[12:13], v[236:237] op_sel_hi:[1,0]
	v_pk_mul_f32 v[14:15], v[14:15], v[236:237] op_sel_hi:[1,0]
	v_pk_mul_f32 v[8:9], v[8:9], v[236:237] op_sel_hi:[1,0]
	v_pk_mul_f32 v[10:11], v[10:11], v[236:237] op_sel_hi:[1,0]
	v_pk_mul_f32 v[12:13], v[12:13], v[200:201]
	v_pk_mul_f32 v[14:15], v[14:15], v[202:203]
	v_pk_mul_f32 v[8:9], v[8:9], v[204:205]
	v_pk_mul_f32 v[10:11], v[10:11], v[206:207]
	v_cvt_pk_bf16_f32 v212, v12, v13
	v_cvt_pk_bf16_f32 v213, v14, v15
	v_cvt_pk_bf16_f32 v214, v8, v9
	v_cvt_pk_bf16_f32 v215, v10, v11
	s_mov_b64 s[100:101], 0xf2000
	v_lshl_add_u64 v[216:217], v[232:233], 0, s[100:101]
	global_store_dwordx4 v[216:217], v[212:215], off
	s_andn2_b64 vcc, exec, s[4:5]
	s_mov_b64 s[4:5], -1
	s_cbranch_vccnz .LBB0_1055
	s_andn2_b64 vcc, exec, s[0:1]
	s_cbranch_vccnz .LBB0_1054
	s_nop 0
	s_branch .LBB0_1054

.LBB0_1650:
	v_lshl_add_u32 v159, s12, 10, v152
	v_lshl_or_b32 v148, s13, 7, v153
	v_lshl_add_u32 v158, s30, 8, v150
	v_ashrrev_i32_e32 v149, 31, v148
	v_mov_b64_e32 v[146:147], s[16:17]
	v_mad_i64_i32 v[162:163], s[12:13], v158, s55, v[146:147]
	v_lshlrev_b64 v[148:149], 1, v[148:149]
	v_lshl_add_u64 v[162:163], v[162:163], 0, v[148:149]
	v_mov_b32_e32 v232, v162
	v_mov_b32_e32 v233, v163
	ds_read_b32 v172, v159
	ds_read_b32 v174, v159 offset:64
	ds_read_b32 v176, v159 offset:128
	ds_read_b32 v178, v159 offset:192
	ds_read_b32 v180, v159 offset:512
	ds_read_b32 v182, v159 offset:576
	ds_read_b32 v184, v159 offset:640
	ds_read_b32 v186, v159 offset:704
	v_mov_b32_e32 v188, 0xbfb8aa3b
	v_mov_b32_e32 v190, 1.0
	v_mov_b32_e32 v191, 1.0
	s_waitcnt lgkmcnt(7)
	v_mul_f32_e32 v234, v188, v172
	v_mul_f32_e32 v236, v172, v172
	v_pk_mul_f32 v[192:193], v[124:125], v[234:235] op_sel_hi:[1,0]
	v_pk_mul_f32 v[194:195], v[126:127], v[234:235] op_sel_hi:[1,0]
	v_pk_mul_f32 v[196:197], v[120:121], v[234:235] op_sel_hi:[1,0]
	v_pk_mul_f32 v[198:199], v[122:123], v[234:235] op_sel_hi:[1,0]
	v_exp_f32_e32 v192, v192
	v_exp_f32_e32 v193, v193
	v_exp_f32_e32 v194, v194
	v_exp_f32_e32 v195, v195
	v_exp_f32_e32 v196, v196
	v_exp_f32_e32 v197, v197
	v_exp_f32_e32 v198, v198
	v_exp_f32_e32 v199, v199
	v_pk_mul_f32 v[124:125], v[124:125], v[116:117]
	v_pk_mul_f32 v[126:127], v[126:127], v[118:119]
	v_pk_mul_f32 v[120:121], v[120:121], v[112:113]
	v_pk_mul_f32 v[122:123], v[122:123], v[114:115]
	v_pk_add_f32 v[192:193], v[192:193], v[190:191]
	v_pk_add_f32 v[194:195], v[194:195], v[190:191]
	v_pk_add_f32 v[196:197], v[196:197], v[190:191]
	v_pk_add_f32 v[198:199], v[198:199], v[190:191]
	v_rcp_f32_e32 v192, v192
	v_rcp_f32_e32 v193, v193
	v_rcp_f32_e32 v194, v194
	v_rcp_f32_e32 v195, v195
	v_rcp_f32_e32 v196, v196
	v_rcp_f32_e32 v197, v197
	v_rcp_f32_e32 v198, v198
	v_rcp_f32_e32 v199, v199
	v_pk_mul_f32 v[124:125], v[124:125], v[236:237] op_sel_hi:[1,0]
	v_pk_mul_f32 v[126:127], v[126:127], v[236:237] op_sel_hi:[1,0]
	v_pk_mul_f32 v[120:121], v[120:121], v[236:237] op_sel_hi:[1,0]
	v_pk_mul_f32 v[122:123], v[122:123], v[236:237] op_sel_hi:[1,0]
	v_pk_mul_f32 v[124:125], v[124:125], v[192:193]
	v_pk_mul_f32 v[126:127], v[126:127], v[194:195]
	v_pk_mul_f32 v[120:121], v[120:121], v[196:197]
	v_pk_mul_f32 v[122:123], v[122:123], v[198:199]
	v_cvt_pk_bf16_f32 v208, v124, v125
	v_cvt_pk_bf16_f32 v209, v126, v127
	v_cvt_pk_bf16_f32 v210, v120, v121
	v_cvt_pk_bf16_f32 v211, v122, v123
	global_store_dwordx4 v[232:233], v[208:211], off
	s_waitcnt lgkmcnt(6)
	v_mul_f32_e32 v234, v188, v174
	v_mul_f32_e32 v236, v174, v174
	v_pk_mul_f32 v[200:201], v[108:109], v[234:235] op_sel_hi:[1,0]
	v_pk_mul_f32 v[202:203], v[110:111], v[234:235] op_sel_hi:[1,0]
	v_pk_mul_f32 v[204:205], v[104:105], v[234:235] op_sel_hi:[1,0]
	v_pk_mul_f32 v[206:207], v[106:107], v[234:235] op_sel_hi:[1,0]
	v_exp_f32_e32 v200, v200
	v_exp_f32_e32 v201, v201
	v_exp_f32_e32 v202, v202
	v_exp_f32_e32 v203, v203
	v_exp_f32_e32 v204, v204
	v_exp_f32_e32 v205, v205
	v_exp_f32_e32 v206, v206
	v_exp_f32_e32 v207, v207
	v_pk_mul_f32 v[108:109], v[108:109], v[100:101]
	v_pk_mul_f32 v[110:111], v[110:111], v[102:103]
	v_pk_mul_f32 v[104:105], v[104:105], v[96:97]
	v_pk_mul_f32 v[106:107], v[106:107], v[98:99]
	v_pk_add_f32 v[200:201], v[200:201], v[190:191]
	v_pk_add_f32 v[202:203], v[202:203], v[190:191]
	v_pk_add_f32 v[204:205], v[204:205], v[190:191]
	v_pk_add_f32 v[206:207], v[206:207], v[190:191]
	v_rcp_f32_e32 v200, v200
	v_rcp_f32_e32 v201, v201
	v_rcp_f32_e32 v202, v202
	v_rcp_f32_e32 v203, v203
	v_rcp_f32_e32 v204, v204
	v_rcp_f32_e32 v205, v205
	v_rcp_f32_e32 v206, v206
	v_rcp_f32_e32 v207, v207
	v_pk_mul_f32 v[108:109], v[108:109], v[236:237] op_sel_hi:[1,0]
	v_pk_mul_f32 v[110:111], v[110:111], v[236:237] op_sel_hi:[1,0]
	v_pk_mul_f32 v[104:105], v[104:105], v[236:237] op_sel_hi:[1,0]
	v_pk_mul_f32 v[106:107], v[106:107], v[236:237] op_sel_hi:[1,0]
	v_pk_mul_f32 v[108:109], v[108:109], v[200:201]
	v_pk_mul_f32 v[110:111], v[110:111], v[202:203]
	v_pk_mul_f32 v[104:105], v[104:105], v[204:205]
	v_pk_mul_f32 v[106:107], v[106:107], v[206:207]
	v_cvt_pk_bf16_f32 v212, v108, v109
	v_cvt_pk_bf16_f32 v213, v110, v111
	v_cvt_pk_bf16_f32 v214, v104, v105
	v_cvt_pk_bf16_f32 v215, v106, v107
	s_mov_b64 s[100:101], 0x16000
	v_lshl_add_u64 v[216:217], v[232:233], 0, s[100:101]
	global_store_dwordx4 v[216:217], v[212:215], off
	s_waitcnt lgkmcnt(5)
	v_mul_f32_e32 v234, v188, v176
	v_mul_f32_e32 v236, v176, v176
	v_pk_mul_f32 v[192:193], v[92:93], v[234:235] op_sel_hi:[1,0]
	v_pk_mul_f32 v[194:195], v[94:95], v[234:235] op_sel_hi:[1,0]
	v_pk_mul_f32 v[196:197], v[88:89], v[234:235] op_sel_hi:[1,0]
	v_pk_mul_f32 v[198:199], v[90:91], v[234:235] op_sel_hi:[1,0]
	v_exp_f32_e32 v192, v192
	v_exp_f32_e32 v193, v193
	v_exp_f32_e32 v194, v194
	v_exp_f32_e32 v195, v195
	v_exp_f32_e32 v196, v196
	v_exp_f32_e32 v197, v197
	v_exp_f32_e32 v198, v198
	v_exp_f32_e32 v199, v199
	v_pk_mul_f32 v[92:93], v[92:93], v[84:85]
	v_pk_mul_f32 v[94:95], v[94:95], v[86:87]
	v_pk_mul_f32 v[88:89], v[88:89], v[80:81]
	v_pk_mul_f32 v[90:91], v[90:91], v[82:83]
	v_pk_add_f32 v[192:193], v[192:193], v[190:191]
	v_pk_add_f32 v[194:195], v[194:195], v[190:191]
	v_pk_add_f32 v[196:197], v[196:197], v[190:191]
	v_pk_add_f32 v[198:199], v[198:199], v[190:191]
	v_rcp_f32_e32 v192, v192
	v_rcp_f32_e32 v193, v193
	v_rcp_f32_e32 v194, v194
	v_rcp_f32_e32 v195, v195
	v_rcp_f32_e32 v196, v196
	v_rcp_f32_e32 v197, v197
	v_rcp_f32_e32 v198, v198
	v_rcp_f32_e32 v199, v199
	v_pk_mul_f32 v[92:93], v[92:93], v[236:237] op_sel_hi:[1,0]
	v_pk_mul_f32 v[94:95], v[94:95], v[236:237] op_sel_hi:[1,0]
	v_pk_mul_f32 v[88:89], v[88:89], v[236:237] op_sel_hi:[1,0]
	v_pk_mul_f32 v[90:91], v[90:91], v[236:237] op_sel_hi:[1,0]
	v_pk_mul_f32 v[92:93], v[92:93], v[192:193]
	v_pk_mul_f32 v[94:95], v[94:95], v[194:195]
	v_pk_mul_f32 v[88:89], v[88:89], v[196:197]
	v_pk_mul_f32 v[90:91], v[90:91], v[198:199]
	v_cvt_pk_bf16_f32 v208, v92, v93
	v_cvt_pk_bf16_f32 v209, v94, v95
	v_cvt_pk_bf16_f32 v210, v88, v89
	v_cvt_pk_bf16_f32 v211, v90, v91
	s_mov_b64 s[100:101], 0x2c000
	v_lshl_add_u64 v[216:217], v[232:233], 0, s[100:101]
	global_store_dwordx4 v[216:217], v[208:211], off
	s_waitcnt lgkmcnt(4)
	v_mul_f32_e32 v234, v188, v178
	v_mul_f32_e32 v236, v178, v178
	v_pk_mul_f32 v[200:201], v[76:77], v[234:235] op_sel_hi:[1,0]
	v_pk_mul_f32 v[202:203], v[78:79], v[234:235] op_sel_hi:[1,0]
	v_pk_mul_f32 v[204:205], v[72:73], v[234:235] op_sel_hi:[1,0]
	v_pk_mul_f32 v[206:207], v[74:75], v[234:235] op_sel_hi:[1,0]
	v_exp_f32_e32 v200, v200
	v_exp_f32_e32 v201, v201
	v_exp_f32_e32 v202, v202
	v_exp_f32_e32 v203, v203
	v_exp_f32_e32 v204, v204
	v_exp_f32_e32 v205, v205
	v_exp_f32_e32 v206, v206
	v_exp_f32_e32 v207, v207
	v_pk_mul_f32 v[76:77], v[76:77], v[68:69]
	v_pk_mul_f32 v[78:79], v[78:79], v[70:71]
	v_pk_mul_f32 v[72:73], v[72:73], v[64:65]
	v_pk_mul_f32 v[74:75], v[74:75], v[66:67]
	v_pk_add_f32 v[200:201], v[200:201], v[190:191]
	v_pk_add_f32 v[202:203], v[202:203], v[190:191]
	v_pk_add_f32 v[204:205], v[204:205], v[190:191]
	v_pk_add_f32 v[206:207], v[206:207], v[190:191]
	v_rcp_f32_e32 v200, v200
	v_rcp_f32_e32 v201, v201
	v_rcp_f32_e32 v202, v202
	v_rcp_f32_e32 v203, v203
	v_rcp_f32_e32 v204, v204
	v_rcp_f32_e32 v205, v205
	v_rcp_f32_e32 v206, v206
	v_rcp_f32_e32 v207, v207
	v_pk_mul_f32 v[76:77], v[76:77], v[236:237] op_sel_hi:[1,0]
	v_pk_mul_f32 v[78:79], v[78:79], v[236:237] op_sel_hi:[1,0]
	v_pk_mul_f32 v[72:73], v[72:73], v[236:237] op_sel_hi:[1,0]
	v_pk_mul_f32 v[74:75], v[74:75], v[236:237] op_sel_hi:[1,0]
	v_pk_mul_f32 v[76:77], v[76:77], v[200:201]
	v_pk_mul_f32 v[78:79], v[78:79], v[202:203]
	v_pk_mul_f32 v[72:73], v[72:73], v[204:205]
	v_pk_mul_f32 v[74:75], v[74:75], v[206:207]
	v_cvt_pk_bf16_f32 v212, v76, v77
	v_cvt_pk_bf16_f32 v213, v78, v79
	v_cvt_pk_bf16_f32 v214, v72, v73
	v_cvt_pk_bf16_f32 v215, v74, v75
	s_mov_b64 s[100:101], 0x42000
	v_lshl_add_u64 v[216:217], v[232:233], 0, s[100:101]
	global_store_dwordx4 v[216:217], v[212:215], off
	s_waitcnt lgkmcnt(3)
	v_mul_f32_e32 v234, v188, v180
	v_mul_f32_e32 v236, v180, v180
	v_pk_mul_f32 v[192:193], v[60:61], v[234:235] op_sel_hi:[1,0]
	v_pk_mul_f32 v[194:195], v[62:63], v[234:235] op_sel_hi:[1,0]
	v_pk_mul_f32 v[196:197], v[56:57], v[234:235] op_sel_hi:[1,0]
	v_pk_mul_f32 v[198:199], v[58:59], v[234:235] op_sel_hi:[1,0]
	v_exp_f32_e32 v192, v192
	v_exp_f32_e32 v193, v193
	v_exp_f32_e32 v194, v194
	v_exp_f32_e32 v195, v195
	v_exp_f32_e32 v196, v196
	v_exp_f32_e32 v197, v197
	v_exp_f32_e32 v198, v198
	v_exp_f32_e32 v199, v199
	v_pk_mul_f32 v[60:61], v[60:61], v[52:53]
	v_pk_mul_f32 v[62:63], v[62:63], v[54:55]
	v_pk_mul_f32 v[56:57], v[56:57], v[48:49]
	v_pk_mul_f32 v[58:59], v[58:59], v[50:51]
	v_pk_add_f32 v[192:193], v[192:193], v[190:191]
	v_pk_add_f32 v[194:195], v[194:195], v[190:191]
	v_pk_add_f32 v[196:197], v[196:197], v[190:191]
	v_pk_add_f32 v[198:199], v[198:199], v[190:191]
	v_rcp_f32_e32 v192, v192
	v_rcp_f32_e32 v193, v193
	v_rcp_f32_e32 v194, v194
	v_rcp_f32_e32 v195, v195
	v_rcp_f32_e32 v196, v196
	v_rcp_f32_e32 v197, v197
	v_rcp_f32_e32 v198, v198
	v_rcp_f32_e32 v199, v199
	v_pk_mul_f32 v[60:61], v[60:61], v[236:237] op_sel_hi:[1,0]
	v_pk_mul_f32 v[62:63], v[62:63], v[236:237] op_sel_hi:[1,0]
	v_pk_mul_f32 v[56:57], v[56:57], v[236:237] op_sel_hi:[1,0]
	v_pk_mul_f32 v[58:59], v[58:59], v[236:237] op_sel_hi:[1,0]
	v_pk_mul_f32 v[60:61], v[60:61], v[192:193]
	v_pk_mul_f32 v[62:63], v[62:63], v[194:195]
	v_pk_mul_f32 v[56:57], v[56:57], v[196:197]
	v_pk_mul_f32 v[58:59], v[58:59], v[198:199]
	v_cvt_pk_bf16_f32 v208, v60, v61
	v_cvt_pk_bf16_f32 v209, v62, v63
	v_cvt_pk_bf16_f32 v210, v56, v57
	v_cvt_pk_bf16_f32 v211, v58, v59
	s_mov_b64 s[100:101], 0xb0000
	v_lshl_add_u64 v[216:217], v[232:233], 0, s[100:101]
	global_store_dwordx4 v[216:217], v[208:211], off
	s_waitcnt lgkmcnt(2)
	v_mul_f32_e32 v234, v188, v182
	v_mul_f32_e32 v236, v182, v182
	v_pk_mul_f32 v[200:201], v[44:45], v[234:235] op_sel_hi:[1,0]
	v_pk_mul_f32 v[202:203], v[46:47], v[234:235] op_sel_hi:[1,0]
	v_pk_mul_f32 v[204:205], v[40:41], v[234:235] op_sel_hi:[1,0]
	v_pk_mul_f32 v[206:207], v[42:43], v[234:235] op_sel_hi:[1,0]
	v_exp_f32_e32 v200, v200
	v_exp_f32_e32 v201, v201
	v_exp_f32_e32 v202, v202
	v_exp_f32_e32 v203, v203
	v_exp_f32_e32 v204, v204
	v_exp_f32_e32 v205, v205
	v_exp_f32_e32 v206, v206
	v_exp_f32_e32 v207, v207
	v_pk_mul_f32 v[44:45], v[44:45], v[36:37]
	v_pk_mul_f32 v[46:47], v[46:47], v[38:39]
	v_pk_mul_f32 v[40:41], v[40:41], v[32:33]
	v_pk_mul_f32 v[42:43], v[42:43], v[34:35]
	v_pk_add_f32 v[200:201], v[200:201], v[190:191]
	v_pk_add_f32 v[202:203], v[202:203], v[190:191]
	v_pk_add_f32 v[204:205], v[204:205], v[190:191]
	v_pk_add_f32 v[206:207], v[206:207], v[190:191]
	v_rcp_f32_e32 v200, v200
	v_rcp_f32_e32 v201, v201
	v_rcp_f32_e32 v202, v202
	v_rcp_f32_e32 v203, v203
	v_rcp_f32_e32 v204, v204
	v_rcp_f32_e32 v205, v205
	v_rcp_f32_e32 v206, v206
	v_rcp_f32_e32 v207, v207
	v_pk_mul_f32 v[44:45], v[44:45], v[236:237] op_sel_hi:[1,0]
	v_pk_mul_f32 v[46:47], v[46:47], v[236:237] op_sel_hi:[1,0]
	v_pk_mul_f32 v[40:41], v[40:41], v[236:237] op_sel_hi:[1,0]
	v_pk_mul_f32 v[42:43], v[42:43], v[236:237] op_sel_hi:[1,0]
	v_pk_mul_f32 v[44:45], v[44:45], v[200:201]
	v_pk_mul_f32 v[46:47], v[46:47], v[202:203]
	v_pk_mul_f32 v[40:41], v[40:41], v[204:205]
	v_pk_mul_f32 v[42:43], v[42:43], v[206:207]
	v_cvt_pk_bf16_f32 v212, v44, v45
	v_cvt_pk_bf16_f32 v213, v46, v47
	v_cvt_pk_bf16_f32 v214, v40, v41
	v_cvt_pk_bf16_f32 v215, v42, v43
	s_mov_b64 s[100:101], 0xc6000
	v_lshl_add_u64 v[216:217], v[232:233], 0, s[100:101]
	global_store_dwordx4 v[216:217], v[212:215], off
	s_waitcnt lgkmcnt(1)
	v_mul_f32_e32 v234, v188, v184
	v_mul_f32_e32 v236, v184, v184
	v_pk_mul_f32 v[192:193], v[28:29], v[234:235] op_sel_hi:[1,0]
	v_pk_mul_f32 v[194:195], v[30:31], v[234:235] op_sel_hi:[1,0]
	v_pk_mul_f32 v[196:197], v[24:25], v[234:235] op_sel_hi:[1,0]
	v_pk_mul_f32 v[198:199], v[26:27], v[234:235] op_sel_hi:[1,0]
	v_exp_f32_e32 v192, v192
	v_exp_f32_e32 v193, v193
	v_exp_f32_e32 v194, v194
	v_exp_f32_e32 v195, v195
	v_exp_f32_e32 v196, v196
	v_exp_f32_e32 v197, v197
	v_exp_f32_e32 v198, v198
	v_exp_f32_e32 v199, v199
	v_pk_mul_f32 v[28:29], v[28:29], v[20:21]
	v_pk_mul_f32 v[30:31], v[30:31], v[22:23]
	v_pk_mul_f32 v[24:25], v[24:25], v[16:17]
	v_pk_mul_f32 v[26:27], v[26:27], v[18:19]
	v_pk_add_f32 v[192:193], v[192:193], v[190:191]
	v_pk_add_f32 v[194:195], v[194:195], v[190:191]
	v_pk_add_f32 v[196:197], v[196:197], v[190:191]
	v_pk_add_f32 v[198:199], v[198:199], v[190:191]
	v_rcp_f32_e32 v192, v192
	v_rcp_f32_e32 v193, v193
	v_rcp_f32_e32 v194, v194
	v_rcp_f32_e32 v195, v195
	v_rcp_f32_e32 v196, v196
	v_rcp_f32_e32 v197, v197
	v_rcp_f32_e32 v198, v198
	v_rcp_f32_e32 v199, v199
	v_pk_mul_f32 v[28:29], v[28:29], v[236:237] op_sel_hi:[1,0]
	v_pk_mul_f32 v[30:31], v[30:31], v[236:237] op_sel_hi:[1,0]
	v_pk_mul_f32 v[24:25], v[24:25], v[236:237] op_sel_hi:[1,0]
	v_pk_mul_f32 v[26:27], v[26:27], v[236:237] op_sel_hi:[1,0]
	v_pk_mul_f32 v[28:29], v[28:29], v[192:193]
	v_pk_mul_f32 v[30:31], v[30:31], v[194:195]
	v_pk_mul_f32 v[24:25], v[24:25], v[196:197]
	v_pk_mul_f32 v[26:27], v[26:27], v[198:199]
	v_cvt_pk_bf16_f32 v208, v28, v29
	v_cvt_pk_bf16_f32 v209, v30, v31
	v_cvt_pk_bf16_f32 v210, v24, v25
	v_cvt_pk_bf16_f32 v211, v26, v27
	s_mov_b64 s[100:101], 0xdc000
	v_lshl_add_u64 v[216:217], v[232:233], 0, s[100:101]
	global_store_dwordx4 v[216:217], v[208:211], off
	s_waitcnt lgkmcnt(0)
	v_mul_f32_e32 v234, v188, v186
	v_mul_f32_e32 v236, v186, v186
	v_pk_mul_f32 v[200:201], v[12:13], v[234:235] op_sel_hi:[1,0]
	v_pk_mul_f32 v[202:203], v[14:15], v[234:235] op_sel_hi:[1,0]
	v_pk_mul_f32 v[204:205], v[8:9], v[234:235] op_sel_hi:[1,0]
	v_pk_mul_f32 v[206:207], v[10:11], v[234:235] op_sel_hi:[1,0]
	v_exp_f32_e32 v200, v200
	v_exp_f32_e32 v201, v201
	v_exp_f32_e32 v202, v202
	v_exp_f32_e32 v203, v203
	v_exp_f32_e32 v204, v204
	v_exp_f32_e32 v205, v205
	v_exp_f32_e32 v206, v206
	v_exp_f32_e32 v207, v207
	v_pk_mul_f32 v[12:13], v[12:13], v[4:5]
	v_pk_mul_f32 v[14:15], v[14:15], v[6:7]
	v_pk_mul_f32 v[8:9], v[8:9], v[0:1]
	v_pk_mul_f32 v[10:11], v[10:11], v[2:3]
	v_pk_add_f32 v[200:201], v[200:201], v[190:191]
	v_pk_add_f32 v[202:203], v[202:203], v[190:191]
	v_pk_add_f32 v[204:205], v[204:205], v[190:191]
	v_pk_add_f32 v[206:207], v[206:207], v[190:191]
	v_rcp_f32_e32 v200, v200
	v_rcp_f32_e32 v201, v201
	v_rcp_f32_e32 v202, v202
	v_rcp_f32_e32 v203, v203
	v_rcp_f32_e32 v204, v204
	v_rcp_f32_e32 v205, v205
	v_rcp_f32_e32 v206, v206
	v_rcp_f32_e32 v207, v207
	v_pk_mul_f32 v[12:13], v[12:13], v[236:237] op_sel_hi:[1,0]
	v_pk_mul_f32 v[14:15], v[14:15], v[236:237] op_sel_hi:[1,0]
	v_pk_mul_f32 v[8:9], v[8:9], v[236:237] op_sel_hi:[1,0]
	v_pk_mul_f32 v[10:11], v[10:11], v[236:237] op_sel_hi:[1,0]
	v_pk_mul_f32 v[12:13], v[12:13], v[200:201]
	v_pk_mul_f32 v[14:15], v[14:15], v[202:203]
	v_pk_mul_f32 v[8:9], v[8:9], v[204:205]
	v_pk_mul_f32 v[10:11], v[10:11], v[206:207]
	v_cvt_pk_bf16_f32 v212, v12, v13
	v_cvt_pk_bf16_f32 v213, v14, v15
	v_cvt_pk_bf16_f32 v214, v8, v9
	v_cvt_pk_bf16_f32 v215, v10, v11
	s_mov_b64 s[100:101], 0xf2000
	v_lshl_add_u64 v[216:217], v[232:233], 0, s[100:101]
	global_store_dwordx4 v[216:217], v[212:215], off
	s_andn2_b64 vcc, exec, s[4:5]
	s_mov_b64 s[4:5], -1
	s_cbranch_vccnz .LBB0_1643
	s_andn2_b64 vcc, exec, s[0:1]
	s_cbranch_vccnz .LBB0_1642
	s_nop 0
	s_branch .LBB0_1642

.LBB0_2094:
	v_lshl_add_u32 v157, s12, 10, v151
	v_lshl_or_b32 v148, s13, 7, v152
	v_lshl_add_u32 v156, s24, 8, v129
	v_ashrrev_i32_e32 v149, 31, v148
	v_mov_b64_e32 v[146:147], s[16:17]
	v_mad_i64_i32 v[160:161], s[12:13], v156, s49, v[146:147]
	v_lshlrev_b64 v[148:149], 1, v[148:149]
	v_lshl_add_u64 v[160:161], v[160:161], 0, v[148:149]
	v_mov_b32_e32 v232, v160
	v_mov_b32_e32 v233, v161
	ds_read_b32 v172, v157
	ds_read_b32 v174, v157 offset:64
	ds_read_b32 v176, v157 offset:128
	ds_read_b32 v178, v157 offset:192
	ds_read_b32 v180, v157 offset:512
	ds_read_b32 v182, v157 offset:576
	ds_read_b32 v184, v157 offset:640
	ds_read_b32 v186, v157 offset:704
	v_mov_b32_e32 v188, 0xbfb8aa3b
	v_mov_b32_e32 v190, 1.0
	v_mov_b32_e32 v191, 1.0
	s_waitcnt lgkmcnt(7)
	v_mul_f32_e32 v234, v188, v172
	v_mul_f32_e32 v236, v172, v172
	v_pk_mul_f32 v[192:193], v[124:125], v[234:235] op_sel_hi:[1,0]
	v_pk_mul_f32 v[194:195], v[126:127], v[234:235] op_sel_hi:[1,0]
	v_pk_mul_f32 v[196:197], v[120:121], v[234:235] op_sel_hi:[1,0]
	v_pk_mul_f32 v[198:199], v[122:123], v[234:235] op_sel_hi:[1,0]
	v_exp_f32_e32 v192, v192
	v_exp_f32_e32 v193, v193
	v_exp_f32_e32 v194, v194
	v_exp_f32_e32 v195, v195
	v_exp_f32_e32 v196, v196
	v_exp_f32_e32 v197, v197
	v_exp_f32_e32 v198, v198
	v_exp_f32_e32 v199, v199
	v_pk_mul_f32 v[124:125], v[124:125], v[116:117]
	v_pk_mul_f32 v[126:127], v[126:127], v[118:119]
	v_pk_mul_f32 v[120:121], v[120:121], v[112:113]
	v_pk_mul_f32 v[122:123], v[122:123], v[114:115]
	v_pk_add_f32 v[192:193], v[192:193], v[190:191]
	v_pk_add_f32 v[194:195], v[194:195], v[190:191]
	v_pk_add_f32 v[196:197], v[196:197], v[190:191]
	v_pk_add_f32 v[198:199], v[198:199], v[190:191]
	v_rcp_f32_e32 v192, v192
	v_rcp_f32_e32 v193, v193
	v_rcp_f32_e32 v194, v194
	v_rcp_f32_e32 v195, v195
	v_rcp_f32_e32 v196, v196
	v_rcp_f32_e32 v197, v197
	v_rcp_f32_e32 v198, v198
	v_rcp_f32_e32 v199, v199
	v_pk_mul_f32 v[124:125], v[124:125], v[236:237] op_sel_hi:[1,0]
	v_pk_mul_f32 v[126:127], v[126:127], v[236:237] op_sel_hi:[1,0]
	v_pk_mul_f32 v[120:121], v[120:121], v[236:237] op_sel_hi:[1,0]
	v_pk_mul_f32 v[122:123], v[122:123], v[236:237] op_sel_hi:[1,0]
	v_pk_mul_f32 v[124:125], v[124:125], v[192:193]
	v_pk_mul_f32 v[126:127], v[126:127], v[194:195]
	v_pk_mul_f32 v[120:121], v[120:121], v[196:197]
	v_pk_mul_f32 v[122:123], v[122:123], v[198:199]
	v_cvt_pk_bf16_f32 v208, v124, v125
	v_cvt_pk_bf16_f32 v209, v126, v127
	v_cvt_pk_bf16_f32 v210, v120, v121
	v_cvt_pk_bf16_f32 v211, v122, v123
	global_store_dwordx4 v[232:233], v[208:211], off
	s_waitcnt lgkmcnt(6)
	v_mul_f32_e32 v234, v188, v174
	v_mul_f32_e32 v236, v174, v174
	v_pk_mul_f32 v[200:201], v[108:109], v[234:235] op_sel_hi:[1,0]
	v_pk_mul_f32 v[202:203], v[110:111], v[234:235] op_sel_hi:[1,0]
	v_pk_mul_f32 v[204:205], v[104:105], v[234:235] op_sel_hi:[1,0]
	v_pk_mul_f32 v[206:207], v[106:107], v[234:235] op_sel_hi:[1,0]
	v_exp_f32_e32 v200, v200
	v_exp_f32_e32 v201, v201
	v_exp_f32_e32 v202, v202
	v_exp_f32_e32 v203, v203
	v_exp_f32_e32 v204, v204
	v_exp_f32_e32 v205, v205
	v_exp_f32_e32 v206, v206
	v_exp_f32_e32 v207, v207
	v_pk_mul_f32 v[108:109], v[108:109], v[100:101]
	v_pk_mul_f32 v[110:111], v[110:111], v[102:103]
	v_pk_mul_f32 v[104:105], v[104:105], v[96:97]
	v_pk_mul_f32 v[106:107], v[106:107], v[98:99]
	v_pk_add_f32 v[200:201], v[200:201], v[190:191]
	v_pk_add_f32 v[202:203], v[202:203], v[190:191]
	v_pk_add_f32 v[204:205], v[204:205], v[190:191]
	v_pk_add_f32 v[206:207], v[206:207], v[190:191]
	v_rcp_f32_e32 v200, v200
	v_rcp_f32_e32 v201, v201
	v_rcp_f32_e32 v202, v202
	v_rcp_f32_e32 v203, v203
	v_rcp_f32_e32 v204, v204
	v_rcp_f32_e32 v205, v205
	v_rcp_f32_e32 v206, v206
	v_rcp_f32_e32 v207, v207
	v_pk_mul_f32 v[108:109], v[108:109], v[236:237] op_sel_hi:[1,0]
	v_pk_mul_f32 v[110:111], v[110:111], v[236:237] op_sel_hi:[1,0]
	v_pk_mul_f32 v[104:105], v[104:105], v[236:237] op_sel_hi:[1,0]
	v_pk_mul_f32 v[106:107], v[106:107], v[236:237] op_sel_hi:[1,0]
	v_pk_mul_f32 v[108:109], v[108:109], v[200:201]
	v_pk_mul_f32 v[110:111], v[110:111], v[202:203]
	v_pk_mul_f32 v[104:105], v[104:105], v[204:205]
	v_pk_mul_f32 v[106:107], v[106:107], v[206:207]
	v_cvt_pk_bf16_f32 v212, v108, v109
	v_cvt_pk_bf16_f32 v213, v110, v111
	v_cvt_pk_bf16_f32 v214, v104, v105
	v_cvt_pk_bf16_f32 v215, v106, v107
	s_mov_b64 s[100:101], 0x16000
	v_lshl_add_u64 v[216:217], v[232:233], 0, s[100:101]
	global_store_dwordx4 v[216:217], v[212:215], off
	s_waitcnt lgkmcnt(5)
	v_mul_f32_e32 v234, v188, v176
	v_mul_f32_e32 v236, v176, v176
	v_pk_mul_f32 v[192:193], v[92:93], v[234:235] op_sel_hi:[1,0]
	v_pk_mul_f32 v[194:195], v[94:95], v[234:235] op_sel_hi:[1,0]
	v_pk_mul_f32 v[196:197], v[88:89], v[234:235] op_sel_hi:[1,0]
	v_pk_mul_f32 v[198:199], v[90:91], v[234:235] op_sel_hi:[1,0]
	v_exp_f32_e32 v192, v192
	v_exp_f32_e32 v193, v193
	v_exp_f32_e32 v194, v194
	v_exp_f32_e32 v195, v195
	v_exp_f32_e32 v196, v196
	v_exp_f32_e32 v197, v197
	v_exp_f32_e32 v198, v198
	v_exp_f32_e32 v199, v199
	v_pk_mul_f32 v[92:93], v[92:93], v[84:85]
	v_pk_mul_f32 v[94:95], v[94:95], v[86:87]
	v_pk_mul_f32 v[88:89], v[88:89], v[80:81]
	v_pk_mul_f32 v[90:91], v[90:91], v[82:83]
	v_pk_add_f32 v[192:193], v[192:193], v[190:191]
	v_pk_add_f32 v[194:195], v[194:195], v[190:191]
	v_pk_add_f32 v[196:197], v[196:197], v[190:191]
	v_pk_add_f32 v[198:199], v[198:199], v[190:191]
	v_rcp_f32_e32 v192, v192
	v_rcp_f32_e32 v193, v193
	v_rcp_f32_e32 v194, v194
	v_rcp_f32_e32 v195, v195
	v_rcp_f32_e32 v196, v196
	v_rcp_f32_e32 v197, v197
	v_rcp_f32_e32 v198, v198
	v_rcp_f32_e32 v199, v199
	v_pk_mul_f32 v[92:93], v[92:93], v[236:237] op_sel_hi:[1,0]
	v_pk_mul_f32 v[94:95], v[94:95], v[236:237] op_sel_hi:[1,0]
	v_pk_mul_f32 v[88:89], v[88:89], v[236:237] op_sel_hi:[1,0]
	v_pk_mul_f32 v[90:91], v[90:91], v[236:237] op_sel_hi:[1,0]
	v_pk_mul_f32 v[92:93], v[92:93], v[192:193]
	v_pk_mul_f32 v[94:95], v[94:95], v[194:195]
	v_pk_mul_f32 v[88:89], v[88:89], v[196:197]
	v_pk_mul_f32 v[90:91], v[90:91], v[198:199]
	v_cvt_pk_bf16_f32 v208, v92, v93
	v_cvt_pk_bf16_f32 v209, v94, v95
	v_cvt_pk_bf16_f32 v210, v88, v89
	v_cvt_pk_bf16_f32 v211, v90, v91
	s_mov_b64 s[100:101], 0x2c000
	v_lshl_add_u64 v[216:217], v[232:233], 0, s[100:101]
	global_store_dwordx4 v[216:217], v[208:211], off
	s_waitcnt lgkmcnt(4)
	v_mul_f32_e32 v234, v188, v178
	v_mul_f32_e32 v236, v178, v178
	v_pk_mul_f32 v[200:201], v[76:77], v[234:235] op_sel_hi:[1,0]
	v_pk_mul_f32 v[202:203], v[78:79], v[234:235] op_sel_hi:[1,0]
	v_pk_mul_f32 v[204:205], v[72:73], v[234:235] op_sel_hi:[1,0]
	v_pk_mul_f32 v[206:207], v[74:75], v[234:235] op_sel_hi:[1,0]
	v_exp_f32_e32 v200, v200
	v_exp_f32_e32 v201, v201
	v_exp_f32_e32 v202, v202
	v_exp_f32_e32 v203, v203
	v_exp_f32_e32 v204, v204
	v_exp_f32_e32 v205, v205
	v_exp_f32_e32 v206, v206
	v_exp_f32_e32 v207, v207
	v_pk_mul_f32 v[76:77], v[76:77], v[68:69]
	v_pk_mul_f32 v[78:79], v[78:79], v[70:71]
	v_pk_mul_f32 v[72:73], v[72:73], v[64:65]
	v_pk_mul_f32 v[74:75], v[74:75], v[66:67]
	v_pk_add_f32 v[200:201], v[200:201], v[190:191]
	v_pk_add_f32 v[202:203], v[202:203], v[190:191]
	v_pk_add_f32 v[204:205], v[204:205], v[190:191]
	v_pk_add_f32 v[206:207], v[206:207], v[190:191]
	v_rcp_f32_e32 v200, v200
	v_rcp_f32_e32 v201, v201
	v_rcp_f32_e32 v202, v202
	v_rcp_f32_e32 v203, v203
	v_rcp_f32_e32 v204, v204
	v_rcp_f32_e32 v205, v205
	v_rcp_f32_e32 v206, v206
	v_rcp_f32_e32 v207, v207
	v_pk_mul_f32 v[76:77], v[76:77], v[236:237] op_sel_hi:[1,0]
	v_pk_mul_f32 v[78:79], v[78:79], v[236:237] op_sel_hi:[1,0]
	v_pk_mul_f32 v[72:73], v[72:73], v[236:237] op_sel_hi:[1,0]
	v_pk_mul_f32 v[74:75], v[74:75], v[236:237] op_sel_hi:[1,0]
	v_pk_mul_f32 v[76:77], v[76:77], v[200:201]
	v_pk_mul_f32 v[78:79], v[78:79], v[202:203]
	v_pk_mul_f32 v[72:73], v[72:73], v[204:205]
	v_pk_mul_f32 v[74:75], v[74:75], v[206:207]
	v_cvt_pk_bf16_f32 v212, v76, v77
	v_cvt_pk_bf16_f32 v213, v78, v79
	v_cvt_pk_bf16_f32 v214, v72, v73
	v_cvt_pk_bf16_f32 v215, v74, v75
	s_mov_b64 s[100:101], 0x42000
	v_lshl_add_u64 v[216:217], v[232:233], 0, s[100:101]
	global_store_dwordx4 v[216:217], v[212:215], off
	s_waitcnt lgkmcnt(3)
	v_mul_f32_e32 v234, v188, v180
	v_mul_f32_e32 v236, v180, v180
	v_pk_mul_f32 v[192:193], v[60:61], v[234:235] op_sel_hi:[1,0]
	v_pk_mul_f32 v[194:195], v[62:63], v[234:235] op_sel_hi:[1,0]
	v_pk_mul_f32 v[196:197], v[56:57], v[234:235] op_sel_hi:[1,0]
	v_pk_mul_f32 v[198:199], v[58:59], v[234:235] op_sel_hi:[1,0]
	v_exp_f32_e32 v192, v192
	v_exp_f32_e32 v193, v193
	v_exp_f32_e32 v194, v194
	v_exp_f32_e32 v195, v195
	v_exp_f32_e32 v196, v196
	v_exp_f32_e32 v197, v197
	v_exp_f32_e32 v198, v198
	v_exp_f32_e32 v199, v199
	v_pk_mul_f32 v[60:61], v[60:61], v[52:53]
	v_pk_mul_f32 v[62:63], v[62:63], v[54:55]
	v_pk_mul_f32 v[56:57], v[56:57], v[48:49]
	v_pk_mul_f32 v[58:59], v[58:59], v[50:51]
	v_pk_add_f32 v[192:193], v[192:193], v[190:191]
	v_pk_add_f32 v[194:195], v[194:195], v[190:191]
	v_pk_add_f32 v[196:197], v[196:197], v[190:191]
	v_pk_add_f32 v[198:199], v[198:199], v[190:191]
	v_rcp_f32_e32 v192, v192
	v_rcp_f32_e32 v193, v193
	v_rcp_f32_e32 v194, v194
	v_rcp_f32_e32 v195, v195
	v_rcp_f32_e32 v196, v196
	v_rcp_f32_e32 v197, v197
	v_rcp_f32_e32 v198, v198
	v_rcp_f32_e32 v199, v199
	v_pk_mul_f32 v[60:61], v[60:61], v[236:237] op_sel_hi:[1,0]
	v_pk_mul_f32 v[62:63], v[62:63], v[236:237] op_sel_hi:[1,0]
	v_pk_mul_f32 v[56:57], v[56:57], v[236:237] op_sel_hi:[1,0]
	v_pk_mul_f32 v[58:59], v[58:59], v[236:237] op_sel_hi:[1,0]
	v_pk_mul_f32 v[60:61], v[60:61], v[192:193]
	v_pk_mul_f32 v[62:63], v[62:63], v[194:195]
	v_pk_mul_f32 v[56:57], v[56:57], v[196:197]
	v_pk_mul_f32 v[58:59], v[58:59], v[198:199]
	v_cvt_pk_bf16_f32 v208, v60, v61
	v_cvt_pk_bf16_f32 v209, v62, v63
	v_cvt_pk_bf16_f32 v210, v56, v57
	v_cvt_pk_bf16_f32 v211, v58, v59
	s_mov_b64 s[100:101], 0xb0000
	v_lshl_add_u64 v[216:217], v[232:233], 0, s[100:101]
	global_store_dwordx4 v[216:217], v[208:211], off
	s_waitcnt lgkmcnt(2)
	v_mul_f32_e32 v234, v188, v182
	v_mul_f32_e32 v236, v182, v182
	v_pk_mul_f32 v[200:201], v[44:45], v[234:235] op_sel_hi:[1,0]
	v_pk_mul_f32 v[202:203], v[46:47], v[234:235] op_sel_hi:[1,0]
	v_pk_mul_f32 v[204:205], v[40:41], v[234:235] op_sel_hi:[1,0]
	v_pk_mul_f32 v[206:207], v[42:43], v[234:235] op_sel_hi:[1,0]
	v_exp_f32_e32 v200, v200
	v_exp_f32_e32 v201, v201
	v_exp_f32_e32 v202, v202
	v_exp_f32_e32 v203, v203
	v_exp_f32_e32 v204, v204
	v_exp_f32_e32 v205, v205
	v_exp_f32_e32 v206, v206
	v_exp_f32_e32 v207, v207
	v_pk_mul_f32 v[44:45], v[44:45], v[36:37]
	v_pk_mul_f32 v[46:47], v[46:47], v[38:39]
	v_pk_mul_f32 v[40:41], v[40:41], v[32:33]
	v_pk_mul_f32 v[42:43], v[42:43], v[34:35]
	v_pk_add_f32 v[200:201], v[200:201], v[190:191]
	v_pk_add_f32 v[202:203], v[202:203], v[190:191]
	v_pk_add_f32 v[204:205], v[204:205], v[190:191]
	v_pk_add_f32 v[206:207], v[206:207], v[190:191]
	v_rcp_f32_e32 v200, v200
	v_rcp_f32_e32 v201, v201
	v_rcp_f32_e32 v202, v202
	v_rcp_f32_e32 v203, v203
	v_rcp_f32_e32 v204, v204
	v_rcp_f32_e32 v205, v205
	v_rcp_f32_e32 v206, v206
	v_rcp_f32_e32 v207, v207
	v_pk_mul_f32 v[44:45], v[44:45], v[236:237] op_sel_hi:[1,0]
	v_pk_mul_f32 v[46:47], v[46:47], v[236:237] op_sel_hi:[1,0]
	v_pk_mul_f32 v[40:41], v[40:41], v[236:237] op_sel_hi:[1,0]
	v_pk_mul_f32 v[42:43], v[42:43], v[236:237] op_sel_hi:[1,0]
	v_pk_mul_f32 v[44:45], v[44:45], v[200:201]
	v_pk_mul_f32 v[46:47], v[46:47], v[202:203]
	v_pk_mul_f32 v[40:41], v[40:41], v[204:205]
	v_pk_mul_f32 v[42:43], v[42:43], v[206:207]
	v_cvt_pk_bf16_f32 v212, v44, v45
	v_cvt_pk_bf16_f32 v213, v46, v47
	v_cvt_pk_bf16_f32 v214, v40, v41
	v_cvt_pk_bf16_f32 v215, v42, v43
	s_mov_b64 s[100:101], 0xc6000
	v_lshl_add_u64 v[216:217], v[232:233], 0, s[100:101]
	global_store_dwordx4 v[216:217], v[212:215], off
	s_waitcnt lgkmcnt(1)
	v_mul_f32_e32 v234, v188, v184
	v_mul_f32_e32 v236, v184, v184
	v_pk_mul_f32 v[192:193], v[28:29], v[234:235] op_sel_hi:[1,0]
	v_pk_mul_f32 v[194:195], v[30:31], v[234:235] op_sel_hi:[1,0]
	v_pk_mul_f32 v[196:197], v[24:25], v[234:235] op_sel_hi:[1,0]
	v_pk_mul_f32 v[198:199], v[26:27], v[234:235] op_sel_hi:[1,0]
	v_exp_f32_e32 v192, v192
	v_exp_f32_e32 v193, v193
	v_exp_f32_e32 v194, v194
	v_exp_f32_e32 v195, v195
	v_exp_f32_e32 v196, v196
	v_exp_f32_e32 v197, v197
	v_exp_f32_e32 v198, v198
	v_exp_f32_e32 v199, v199
	v_pk_mul_f32 v[28:29], v[28:29], v[20:21]
	v_pk_mul_f32 v[30:31], v[30:31], v[22:23]
	v_pk_mul_f32 v[24:25], v[24:25], v[16:17]
	v_pk_mul_f32 v[26:27], v[26:27], v[18:19]
	v_pk_add_f32 v[192:193], v[192:193], v[190:191]
	v_pk_add_f32 v[194:195], v[194:195], v[190:191]
	v_pk_add_f32 v[196:197], v[196:197], v[190:191]
	v_pk_add_f32 v[198:199], v[198:199], v[190:191]
	v_rcp_f32_e32 v192, v192
	v_rcp_f32_e32 v193, v193
	v_rcp_f32_e32 v194, v194
	v_rcp_f32_e32 v195, v195
	v_rcp_f32_e32 v196, v196
	v_rcp_f32_e32 v197, v197
	v_rcp_f32_e32 v198, v198
	v_rcp_f32_e32 v199, v199
	v_pk_mul_f32 v[28:29], v[28:29], v[236:237] op_sel_hi:[1,0]
	v_pk_mul_f32 v[30:31], v[30:31], v[236:237] op_sel_hi:[1,0]
	v_pk_mul_f32 v[24:25], v[24:25], v[236:237] op_sel_hi:[1,0]
	v_pk_mul_f32 v[26:27], v[26:27], v[236:237] op_sel_hi:[1,0]
	v_pk_mul_f32 v[28:29], v[28:29], v[192:193]
	v_pk_mul_f32 v[30:31], v[30:31], v[194:195]
	v_pk_mul_f32 v[24:25], v[24:25], v[196:197]
	v_pk_mul_f32 v[26:27], v[26:27], v[198:199]
	v_cvt_pk_bf16_f32 v208, v28, v29
	v_cvt_pk_bf16_f32 v209, v30, v31
	v_cvt_pk_bf16_f32 v210, v24, v25
	v_cvt_pk_bf16_f32 v211, v26, v27
	s_mov_b64 s[100:101], 0xdc000
	v_lshl_add_u64 v[216:217], v[232:233], 0, s[100:101]
	global_store_dwordx4 v[216:217], v[208:211], off
	s_waitcnt lgkmcnt(0)
	v_mul_f32_e32 v234, v188, v186
	v_mul_f32_e32 v236, v186, v186
	v_pk_mul_f32 v[200:201], v[12:13], v[234:235] op_sel_hi:[1,0]
	v_pk_mul_f32 v[202:203], v[14:15], v[234:235] op_sel_hi:[1,0]
	v_pk_mul_f32 v[204:205], v[8:9], v[234:235] op_sel_hi:[1,0]
	v_pk_mul_f32 v[206:207], v[10:11], v[234:235] op_sel_hi:[1,0]
	v_exp_f32_e32 v200, v200
	v_exp_f32_e32 v201, v201
	v_exp_f32_e32 v202, v202
	v_exp_f32_e32 v203, v203
	v_exp_f32_e32 v204, v204
	v_exp_f32_e32 v205, v205
	v_exp_f32_e32 v206, v206
	v_exp_f32_e32 v207, v207
	v_pk_mul_f32 v[12:13], v[12:13], v[4:5]
	v_pk_mul_f32 v[14:15], v[14:15], v[6:7]
	v_pk_mul_f32 v[8:9], v[8:9], v[0:1]
	v_pk_mul_f32 v[10:11], v[10:11], v[2:3]
	v_pk_add_f32 v[200:201], v[200:201], v[190:191]
	v_pk_add_f32 v[202:203], v[202:203], v[190:191]
	v_pk_add_f32 v[204:205], v[204:205], v[190:191]
	v_pk_add_f32 v[206:207], v[206:207], v[190:191]
	v_rcp_f32_e32 v200, v200
	v_rcp_f32_e32 v201, v201
	v_rcp_f32_e32 v202, v202
	v_rcp_f32_e32 v203, v203
	v_rcp_f32_e32 v204, v204
	v_rcp_f32_e32 v205, v205
	v_rcp_f32_e32 v206, v206
	v_rcp_f32_e32 v207, v207
	v_pk_mul_f32 v[12:13], v[12:13], v[236:237] op_sel_hi:[1,0]
	v_pk_mul_f32 v[14:15], v[14:15], v[236:237] op_sel_hi:[1,0]
	v_pk_mul_f32 v[8:9], v[8:9], v[236:237] op_sel_hi:[1,0]
	v_pk_mul_f32 v[10:11], v[10:11], v[236:237] op_sel_hi:[1,0]
	v_pk_mul_f32 v[12:13], v[12:13], v[200:201]
	v_pk_mul_f32 v[14:15], v[14:15], v[202:203]
	v_pk_mul_f32 v[8:9], v[8:9], v[204:205]
	v_pk_mul_f32 v[10:11], v[10:11], v[206:207]
	v_cvt_pk_bf16_f32 v212, v12, v13
	v_cvt_pk_bf16_f32 v213, v14, v15
	v_cvt_pk_bf16_f32 v214, v8, v9
	v_cvt_pk_bf16_f32 v215, v10, v11
	s_mov_b64 s[100:101], 0xf2000
	v_lshl_add_u64 v[216:217], v[232:233], 0, s[100:101]
	global_store_dwordx4 v[216:217], v[212:215], off
	s_andn2_b64 vcc, exec, s[4:5]
	s_mov_b64 s[4:5], -1
	s_cbranch_vccnz .LBB0_2087
	s_andn2_b64 vcc, exec, s[0:1]
	s_cbranch_vccnz .LBB0_2086
	s_nop 0
	s_branch .LBB0_2086
